# x10 + P9 dot products on packed fma (72 instead of 128 VALU per batch)
# speedup vs baseline: 1.0165x; 1.0006x over previous
.LBB0_3585:
	s_or_b64 exec, exec, s[0:1]
	v_mov_b32_e32 v2, 2.0
	v_mov_b32_e32 v3, 0x40100000
	v_mov_b32_e32 v4, 0x40200000
	v_mov_b32_e32 v5, 0x40300000
	v_mov_b32_e32 v6, 0x40400000
	v_mov_b32_e32 v7, 0x40500000
	v_mov_b32_e32 v8, 0x40600000
	v_mov_b32_e32 v9, 0x40700000
	v_mov_b32_e32 v10, 4.0
	v_mov_b32_e32 v11, 0x40900000
	v_mov_b32_e32 v12, 0x40a00000
	v_mov_b32_e32 v13, 0x40b00000
	v_mov_b32_e32 v14, 0x40c00000
	v_mov_b32_e32 v15, 0x40d00000
	v_mov_b32_e32 v16, 0x40e00000
	v_mov_b32_e32 v17, 0x40f00000
	v_mov_b32_e32 v18, 0
	v_mov_b32_e32 v19, 0x3e000000
	v_mov_b32_e32 v20, 0x3e800000
	v_mov_b32_e32 v21, 0x3ec00000
	v_mov_b32_e32 v22, 0.5
	v_mov_b32_e32 v23, 0x3f200000
	v_mov_b32_e32 v24, 0x3f400000
	v_mov_b32_e32 v25, 0x3f600000
	v_mov_b32_e32 v26, 1.0
	v_mov_b32_e32 v27, 0x3f900000
	v_mov_b32_e32 v28, 0x3fa00000
	v_mov_b32_e32 v29, 0x3fb00000
	v_mov_b32_e32 v30, 0x3fc00000
	v_mov_b32_e32 v31, 0x3fd00000
	v_mov_b32_e32 v32, 0x3fe00000
	v_mov_b32_e32 v33, 0x3ff00000
	v_cvt_scalef32_2xpk16_fp6_f32 v[34:39], v[18:33], v[2:17], 1.0
	s_waitcnt lgkmcnt(0)
	s_barrier
	v_cvt_scalef32_pk32_f32_fp6 v[2:33], v[34:39], 1.0
	v_bfe_i32 v34, v0, 0, 1
	v_and_b32_e32 v34, 16, v34
	v_cmp_eq_u32_e32 vcc, 1, v34
	v_and_b32_e32 v1, 1, v0
	v_cmp_eq_u32_e64 s[0:1], 0, v1
	v_cndmask_b32_e32 v35, v2, v3, vcc
	v_cmp_eq_u32_e32 vcc, 2, v34
	s_nop 1
	v_cndmask_b32_e32 v35, v35, v4, vcc
	v_cmp_eq_u32_e32 vcc, 3, v34
	s_nop 1
	v_cndmask_b32_e32 v35, v35, v5, vcc
	v_cmp_eq_u32_e32 vcc, 4, v34
	s_nop 1
	v_cndmask_b32_e32 v35, v35, v6, vcc
	v_cmp_eq_u32_e32 vcc, 5, v34
	s_nop 1
	v_cndmask_b32_e32 v35, v35, v7, vcc
	v_cmp_eq_u32_e32 vcc, 6, v34
	s_nop 1
	v_cndmask_b32_e32 v35, v35, v8, vcc
	v_cmp_eq_u32_e32 vcc, 7, v34
	s_nop 1
	v_cndmask_b32_e32 v35, v35, v9, vcc
	v_cmp_eq_u32_e32 vcc, 8, v34
	s_nop 1
	v_cndmask_b32_e32 v35, v35, v10, vcc
	v_cmp_eq_u32_e32 vcc, 9, v34
	s_nop 1
	v_cndmask_b32_e32 v35, v35, v11, vcc
	v_cmp_eq_u32_e32 vcc, 10, v34
	s_nop 1
	v_cndmask_b32_e32 v35, v35, v12, vcc
	v_cmp_eq_u32_e32 vcc, 11, v34
	s_nop 1
	v_cndmask_b32_e32 v35, v35, v13, vcc
	v_cmp_eq_u32_e32 vcc, 12, v34
	s_nop 1
	v_cndmask_b32_e32 v35, v35, v14, vcc
	v_cmp_eq_u32_e32 vcc, 13, v34
	s_nop 1
	v_cndmask_b32_e32 v35, v35, v15, vcc
	v_cmp_eq_u32_e32 vcc, 14, v34
	s_nop 1
	v_cndmask_b32_e32 v35, v35, v16, vcc
	v_cmp_eq_u32_e32 vcc, 15, v34
	s_nop 1
	v_cndmask_b32_e32 v35, v35, v17, vcc
	v_cmp_eq_u32_e32 vcc, 1, v1
	s_nop 1
	v_cndmask_b32_e32 v1, v35, v18, vcc
	v_cmp_eq_u32_e32 vcc, 17, v34
	s_nop 1
	v_cndmask_b32_e32 v1, v1, v19, vcc
	v_cmp_eq_u32_e32 vcc, 18, v34
	s_nop 1
	v_cndmask_b32_e32 v1, v1, v20, vcc
	v_cmp_eq_u32_e32 vcc, 19, v34
	s_nop 1
	v_cndmask_b32_e32 v1, v1, v21, vcc
	v_cmp_eq_u32_e32 vcc, 20, v34
	s_nop 1
	v_cndmask_b32_e32 v1, v1, v22, vcc
	v_cmp_eq_u32_e32 vcc, 21, v34
	s_nop 1
	v_cndmask_b32_e32 v1, v1, v23, vcc
	v_cmp_eq_u32_e32 vcc, 22, v34
	s_nop 1
	v_cndmask_b32_e32 v1, v1, v24, vcc
	v_cmp_eq_u32_e32 vcc, 23, v34
	s_nop 1
	v_cndmask_b32_e32 v1, v1, v25, vcc
	v_cmp_eq_u32_e32 vcc, 24, v34
	s_nop 1
	v_cndmask_b32_e32 v1, v1, v26, vcc
	v_cmp_eq_u32_e32 vcc, 25, v34
	s_nop 1
	v_cndmask_b32_e32 v1, v1, v27, vcc
	v_cmp_eq_u32_e32 vcc, 26, v34
	s_nop 1
	v_cndmask_b32_e32 v1, v1, v28, vcc
	v_cmp_eq_u32_e32 vcc, 27, v34
	s_nop 1
	v_cndmask_b32_e32 v1, v1, v29, vcc
	v_cmp_eq_u32_e32 vcc, 28, v34
	s_nop 1
	v_cndmask_b32_e32 v1, v1, v30, vcc
	v_cmp_eq_u32_e32 vcc, 29, v34
	s_nop 1
	v_cndmask_b32_e32 v1, v1, v31, vcc
	v_cmp_eq_u32_e32 vcc, 30, v34
	s_nop 1
	v_cndmask_b32_e32 v1, v1, v32, vcc
	v_cmp_eq_u32_e32 vcc, 31, v34
	s_nop 1
	v_cndmask_b32_e32 v34, v1, v33, vcc
	v_cmp_ngt_f32_e32 vcc, 1.0, v34
	s_and_saveexec_b64 s[2:3], vcc
	v_readlane_b32 s68, v251, 51
	s_xor_b64 s[2:3], exec, s[2:3]
	v_readlane_b32 s69, v251, 52
	v_readlane_b32 s74, v251, 57
	v_readlane_b32 s75, v251, 58
	v_readlane_b32 s78, v251, 61
	v_readlane_b32 s79, v251, 62
	v_readlane_b32 s80, v251, 63
	v_readlane_b32 s81, v252, 0
	v_readlane_b32 s82, v252, 1
	v_readlane_b32 s83, v252, 2
	v_readlane_b32 s70, v251, 53
	v_readlane_b32 s71, v251, 54
	v_readlane_b32 s72, v251, 55
	v_readlane_b32 s73, v251, 56
	v_readlane_b32 s76, v251, 59
	v_readlane_b32 s77, v251, 60
	v_lshrrev_b32_e32 v1, 20, v34
	v_add_u32_e32 v1, 0xfffffc10, v1
	s_andn2_saveexec_b64 s[2:3], s[2:3]
	v_mul_f32_e32 v1, 0x41000000, v34
	v_cvt_i32_f32_e32 v1, v1
	s_or_b64 exec, exec, s[2:3]
	v_cndmask_b32_e64 v34, 17, 1, s[0:1]
	v_cmp_eq_u32_e32 vcc, 1, v34
	s_nop 1
	v_cndmask_b32_e32 v35, v2, v3, vcc
	v_cmp_eq_u32_e32 vcc, 2, v34
	s_nop 1
	v_cndmask_b32_e32 v35, v35, v4, vcc
	v_cmp_eq_u32_e32 vcc, 3, v34
	s_nop 1
	v_cndmask_b32_e32 v35, v35, v5, vcc
	v_cmp_eq_u32_e32 vcc, 4, v34
	s_nop 1
	v_cndmask_b32_e32 v35, v35, v6, vcc
	v_cmp_eq_u32_e32 vcc, 5, v34
	s_nop 1
	v_cndmask_b32_e32 v35, v35, v7, vcc
	v_cmp_eq_u32_e32 vcc, 6, v34
	s_nop 1
	v_cndmask_b32_e32 v35, v35, v8, vcc
	v_cmp_eq_u32_e32 vcc, 7, v34
	s_nop 1
	v_cndmask_b32_e32 v35, v35, v9, vcc
	v_cmp_eq_u32_e32 vcc, 8, v34
	s_nop 1
	v_cndmask_b32_e32 v35, v35, v10, vcc
	v_cmp_eq_u32_e32 vcc, 9, v34
	s_nop 1
	v_cndmask_b32_e32 v35, v35, v11, vcc
	v_cmp_eq_u32_e32 vcc, 10, v34
	s_nop 1
	v_cndmask_b32_e32 v35, v35, v12, vcc
	v_cmp_eq_u32_e32 vcc, 11, v34
	s_nop 1
	v_cndmask_b32_e32 v35, v35, v13, vcc
	v_cmp_eq_u32_e32 vcc, 12, v34
	s_nop 1
	v_cndmask_b32_e32 v35, v35, v14, vcc
	v_cmp_eq_u32_e32 vcc, 13, v34
	s_nop 1
	v_cndmask_b32_e32 v35, v35, v15, vcc
	v_cmp_eq_u32_e32 vcc, 14, v34
	s_nop 1
	v_cndmask_b32_e32 v35, v35, v16, vcc
	v_cmp_eq_u32_e32 vcc, 15, v34
	s_nop 1
	v_cndmask_b32_e32 v35, v35, v17, vcc
	v_cmp_eq_u32_e32 vcc, 16, v34
	s_nop 1
	v_cndmask_b32_e32 v35, v35, v18, vcc
	v_cmp_eq_u32_e32 vcc, 17, v34
	s_nop 1
	v_cndmask_b32_e32 v35, v35, v19, vcc
	v_cmp_eq_u32_e32 vcc, 18, v34
	s_nop 1
	v_cndmask_b32_e32 v35, v35, v20, vcc
	v_cmp_eq_u32_e32 vcc, 19, v34
	s_nop 1
	v_cndmask_b32_e32 v35, v35, v21, vcc
	v_cmp_eq_u32_e32 vcc, 20, v34
	s_nop 1
	v_cndmask_b32_e32 v35, v35, v22, vcc
	v_cmp_eq_u32_e32 vcc, 21, v34
	s_nop 1
	v_cndmask_b32_e32 v35, v35, v23, vcc
	v_cmp_eq_u32_e32 vcc, 22, v34
	s_nop 1
	v_cndmask_b32_e32 v35, v35, v24, vcc
	v_cmp_eq_u32_e32 vcc, 23, v34
	s_nop 1
	v_cndmask_b32_e32 v35, v35, v25, vcc
	v_cmp_eq_u32_e32 vcc, 24, v34
	s_nop 1
	v_cndmask_b32_e32 v35, v35, v26, vcc
	v_cmp_eq_u32_e32 vcc, 25, v34
	s_nop 1
	v_cndmask_b32_e32 v35, v35, v27, vcc
	v_cmp_eq_u32_e32 vcc, 26, v34
	s_nop 1
	v_cndmask_b32_e32 v35, v35, v28, vcc
	v_cmp_eq_u32_e32 vcc, 27, v34
	s_nop 1
	v_cndmask_b32_e32 v35, v35, v29, vcc
	v_cmp_eq_u32_e32 vcc, 28, v34
	s_nop 1
	v_cndmask_b32_e32 v35, v35, v30, vcc
	v_cmp_eq_u32_e32 vcc, 29, v34
	s_nop 1
	v_cndmask_b32_e32 v35, v35, v31, vcc
	v_cmp_eq_u32_e32 vcc, 30, v34
	s_nop 1
	v_cndmask_b32_e32 v35, v35, v32, vcc
	v_cmp_eq_u32_e32 vcc, 31, v34
	s_nop 1
	v_cndmask_b32_e32 v35, v35, v33, vcc
	v_cmp_ngt_f32_e32 vcc, 1.0, v35
	s_and_saveexec_b64 s[2:3], vcc
	s_xor_b64 s[2:3], exec, s[2:3]
	v_lshrrev_b32_e32 v34, 20, v35
	v_add_u32_e32 v34, 0xfffffc10, v34
	s_andn2_saveexec_b64 s[2:3], s[2:3]
	v_mul_f32_e32 v34, 0x41000000, v35
	v_cvt_i32_f32_e32 v34, v34
	s_or_b64 exec, exec, s[2:3]
	v_cndmask_b32_e64 v35, 18, 2, s[0:1]
	v_cmp_eq_u32_e32 vcc, 1, v35
	s_nop 1
	v_cndmask_b32_e32 v36, v2, v3, vcc
	v_cmp_eq_u32_e32 vcc, 2, v35
	s_nop 1
	v_cndmask_b32_e32 v36, v36, v4, vcc
	v_cmp_eq_u32_e32 vcc, 3, v35
	s_nop 1
	v_cndmask_b32_e32 v36, v36, v5, vcc
	v_cmp_eq_u32_e32 vcc, 4, v35
	s_nop 1
	v_cndmask_b32_e32 v36, v36, v6, vcc
	v_cmp_eq_u32_e32 vcc, 5, v35
	s_nop 1
	v_cndmask_b32_e32 v36, v36, v7, vcc
	v_cmp_eq_u32_e32 vcc, 6, v35
	s_nop 1
	v_cndmask_b32_e32 v36, v36, v8, vcc
	v_cmp_eq_u32_e32 vcc, 7, v35
	s_nop 1
	v_cndmask_b32_e32 v36, v36, v9, vcc
	v_cmp_eq_u32_e32 vcc, 8, v35
	s_nop 1
	v_cndmask_b32_e32 v36, v36, v10, vcc
	v_cmp_eq_u32_e32 vcc, 9, v35
	s_nop 1
	v_cndmask_b32_e32 v36, v36, v11, vcc
	v_cmp_eq_u32_e32 vcc, 10, v35
	s_nop 1
	v_cndmask_b32_e32 v36, v36, v12, vcc
	v_cmp_eq_u32_e32 vcc, 11, v35
	s_nop 1
	v_cndmask_b32_e32 v36, v36, v13, vcc
	v_cmp_eq_u32_e32 vcc, 12, v35
	s_nop 1
	v_cndmask_b32_e32 v36, v36, v14, vcc
	v_cmp_eq_u32_e32 vcc, 13, v35
	s_nop 1
	v_cndmask_b32_e32 v36, v36, v15, vcc
	v_cmp_eq_u32_e32 vcc, 14, v35
	s_nop 1
	v_cndmask_b32_e32 v36, v36, v16, vcc
	v_cmp_eq_u32_e32 vcc, 15, v35
	s_nop 1
	v_cndmask_b32_e32 v36, v36, v17, vcc
	v_cmp_eq_u32_e32 vcc, 16, v35
	s_nop 1
	v_cndmask_b32_e32 v36, v36, v18, vcc
	v_cmp_eq_u32_e32 vcc, 17, v35
	s_nop 1
	v_cndmask_b32_e32 v36, v36, v19, vcc
	v_cmp_eq_u32_e32 vcc, 18, v35
	s_nop 1
	v_cndmask_b32_e32 v36, v36, v20, vcc
	v_cmp_eq_u32_e32 vcc, 19, v35
	s_nop 1
	v_cndmask_b32_e32 v36, v36, v21, vcc
	v_cmp_eq_u32_e32 vcc, 20, v35
	s_nop 1
	v_cndmask_b32_e32 v36, v36, v22, vcc
	v_cmp_eq_u32_e32 vcc, 21, v35
	s_nop 1
	v_cndmask_b32_e32 v36, v36, v23, vcc
	v_cmp_eq_u32_e32 vcc, 22, v35
	s_nop 1
	v_cndmask_b32_e32 v36, v36, v24, vcc
	v_cmp_eq_u32_e32 vcc, 23, v35
	s_nop 1
	v_cndmask_b32_e32 v36, v36, v25, vcc
	v_cmp_eq_u32_e32 vcc, 24, v35
	s_nop 1
	v_cndmask_b32_e32 v36, v36, v26, vcc
	v_cmp_eq_u32_e32 vcc, 25, v35
	s_nop 1
	v_cndmask_b32_e32 v36, v36, v27, vcc
	v_cmp_eq_u32_e32 vcc, 26, v35
	s_nop 1
	v_cndmask_b32_e32 v36, v36, v28, vcc
	v_cmp_eq_u32_e32 vcc, 27, v35
	s_nop 1
	v_cndmask_b32_e32 v36, v36, v29, vcc
	v_cmp_eq_u32_e32 vcc, 28, v35
	s_nop 1
	v_cndmask_b32_e32 v36, v36, v30, vcc
	v_cmp_eq_u32_e32 vcc, 29, v35
	s_nop 1
	v_cndmask_b32_e32 v36, v36, v31, vcc
	v_cmp_eq_u32_e32 vcc, 30, v35
	s_nop 1
	v_cndmask_b32_e32 v36, v36, v32, vcc
	v_cmp_eq_u32_e32 vcc, 31, v35
	s_nop 1
	v_cndmask_b32_e32 v36, v36, v33, vcc
	v_cmp_ngt_f32_e32 vcc, 1.0, v36
	s_and_saveexec_b64 s[2:3], vcc
	s_xor_b64 s[2:3], exec, s[2:3]
	v_lshrrev_b32_e32 v35, 20, v36
	v_add_u32_e32 v35, 0xfffffc10, v35
	s_andn2_saveexec_b64 s[2:3], s[2:3]
	v_mul_f32_e32 v35, 0x41000000, v36
	v_cvt_i32_f32_e32 v35, v35
	s_or_b64 exec, exec, s[2:3]
	v_cndmask_b32_e64 v36, 19, 3, s[0:1]
	v_cmp_eq_u32_e32 vcc, 1, v36
	s_nop 1
	v_cndmask_b32_e32 v37, v2, v3, vcc
	v_cmp_eq_u32_e32 vcc, 2, v36
	s_nop 1
	v_cndmask_b32_e32 v37, v37, v4, vcc
	v_cmp_eq_u32_e32 vcc, 3, v36
	s_nop 1
	v_cndmask_b32_e32 v37, v37, v5, vcc
	v_cmp_eq_u32_e32 vcc, 4, v36
	s_nop 1
	v_cndmask_b32_e32 v37, v37, v6, vcc
	v_cmp_eq_u32_e32 vcc, 5, v36
	s_nop 1
	v_cndmask_b32_e32 v37, v37, v7, vcc
	v_cmp_eq_u32_e32 vcc, 6, v36
	s_nop 1
	v_cndmask_b32_e32 v37, v37, v8, vcc
	v_cmp_eq_u32_e32 vcc, 7, v36
	s_nop 1
	v_cndmask_b32_e32 v37, v37, v9, vcc
	v_cmp_eq_u32_e32 vcc, 8, v36
	s_nop 1
	v_cndmask_b32_e32 v37, v37, v10, vcc
	v_cmp_eq_u32_e32 vcc, 9, v36
	s_nop 1
	v_cndmask_b32_e32 v37, v37, v11, vcc
	v_cmp_eq_u32_e32 vcc, 10, v36
	s_nop 1
	v_cndmask_b32_e32 v37, v37, v12, vcc
	v_cmp_eq_u32_e32 vcc, 11, v36
	s_nop 1
	v_cndmask_b32_e32 v37, v37, v13, vcc
	v_cmp_eq_u32_e32 vcc, 12, v36
	s_nop 1
	v_cndmask_b32_e32 v37, v37, v14, vcc
	v_cmp_eq_u32_e32 vcc, 13, v36
	s_nop 1
	v_cndmask_b32_e32 v37, v37, v15, vcc
	v_cmp_eq_u32_e32 vcc, 14, v36
	s_nop 1
	v_cndmask_b32_e32 v37, v37, v16, vcc
	v_cmp_eq_u32_e32 vcc, 15, v36
	s_nop 1
	v_cndmask_b32_e32 v37, v37, v17, vcc
	v_cmp_eq_u32_e32 vcc, 16, v36
	s_nop 1
	v_cndmask_b32_e32 v37, v37, v18, vcc
	v_cmp_eq_u32_e32 vcc, 17, v36
	s_nop 1
	v_cndmask_b32_e32 v37, v37, v19, vcc
	v_cmp_eq_u32_e32 vcc, 18, v36
	s_nop 1
	v_cndmask_b32_e32 v37, v37, v20, vcc
	v_cmp_eq_u32_e32 vcc, 19, v36
	s_nop 1
	v_cndmask_b32_e32 v37, v37, v21, vcc
	v_cmp_eq_u32_e32 vcc, 20, v36
	s_nop 1
	v_cndmask_b32_e32 v37, v37, v22, vcc
	v_cmp_eq_u32_e32 vcc, 21, v36
	s_nop 1
	v_cndmask_b32_e32 v37, v37, v23, vcc
	v_cmp_eq_u32_e32 vcc, 22, v36
	s_nop 1
	v_cndmask_b32_e32 v37, v37, v24, vcc
	v_cmp_eq_u32_e32 vcc, 23, v36
	s_nop 1
	v_cndmask_b32_e32 v37, v37, v25, vcc
	v_cmp_eq_u32_e32 vcc, 24, v36
	s_nop 1
	v_cndmask_b32_e32 v37, v37, v26, vcc
	v_cmp_eq_u32_e32 vcc, 25, v36
	s_nop 1
	v_cndmask_b32_e32 v37, v37, v27, vcc
	v_cmp_eq_u32_e32 vcc, 26, v36
	s_nop 1
	v_cndmask_b32_e32 v37, v37, v28, vcc
	v_cmp_eq_u32_e32 vcc, 27, v36
	s_nop 1
	v_cndmask_b32_e32 v37, v37, v29, vcc
	v_cmp_eq_u32_e32 vcc, 28, v36
	s_nop 1
	v_cndmask_b32_e32 v37, v37, v30, vcc
	v_cmp_eq_u32_e32 vcc, 29, v36
	s_nop 1
	v_cndmask_b32_e32 v37, v37, v31, vcc
	v_cmp_eq_u32_e32 vcc, 30, v36
	s_nop 1
	v_cndmask_b32_e32 v37, v37, v32, vcc
	v_cmp_eq_u32_e32 vcc, 31, v36
	s_nop 1
	v_cndmask_b32_e32 v37, v37, v33, vcc
	v_cmp_ngt_f32_e32 vcc, 1.0, v37
	s_and_saveexec_b64 s[2:3], vcc
	s_xor_b64 s[2:3], exec, s[2:3]
	v_lshrrev_b32_e32 v36, 20, v37
	v_add_u32_e32 v36, 0xfffffc10, v36
	s_andn2_saveexec_b64 s[2:3], s[2:3]
	v_mul_f32_e32 v36, 0x41000000, v37
	v_cvt_i32_f32_e32 v36, v36
	s_or_b64 exec, exec, s[2:3]
	v_cndmask_b32_e64 v37, 20, 4, s[0:1]
	v_cmp_eq_u32_e32 vcc, 1, v37
	s_nop 1
	v_cndmask_b32_e32 v38, v2, v3, vcc
	v_cmp_eq_u32_e32 vcc, 2, v37
	s_nop 1
	v_cndmask_b32_e32 v38, v38, v4, vcc
	v_cmp_eq_u32_e32 vcc, 3, v37
	s_nop 1
	v_cndmask_b32_e32 v38, v38, v5, vcc
	v_cmp_eq_u32_e32 vcc, 4, v37
	s_nop 1
	v_cndmask_b32_e32 v38, v38, v6, vcc
	v_cmp_eq_u32_e32 vcc, 5, v37
	s_nop 1
	v_cndmask_b32_e32 v38, v38, v7, vcc
	v_cmp_eq_u32_e32 vcc, 6, v37
	s_nop 1
	v_cndmask_b32_e32 v38, v38, v8, vcc
	v_cmp_eq_u32_e32 vcc, 7, v37
	s_nop 1
	v_cndmask_b32_e32 v38, v38, v9, vcc
	v_cmp_eq_u32_e32 vcc, 8, v37
	s_nop 1
	v_cndmask_b32_e32 v38, v38, v10, vcc
	v_cmp_eq_u32_e32 vcc, 9, v37
	s_nop 1
	v_cndmask_b32_e32 v38, v38, v11, vcc
	v_cmp_eq_u32_e32 vcc, 10, v37
	s_nop 1
	v_cndmask_b32_e32 v38, v38, v12, vcc
	v_cmp_eq_u32_e32 vcc, 11, v37
	s_nop 1
	v_cndmask_b32_e32 v38, v38, v13, vcc
	v_cmp_eq_u32_e32 vcc, 12, v37
	s_nop 1
	v_cndmask_b32_e32 v38, v38, v14, vcc
	v_cmp_eq_u32_e32 vcc, 13, v37
	s_nop 1
	v_cndmask_b32_e32 v38, v38, v15, vcc
	v_cmp_eq_u32_e32 vcc, 14, v37
	s_nop 1
	v_cndmask_b32_e32 v38, v38, v16, vcc
	v_cmp_eq_u32_e32 vcc, 15, v37
	s_nop 1
	v_cndmask_b32_e32 v38, v38, v17, vcc
	v_cmp_eq_u32_e32 vcc, 16, v37
	s_nop 1
	v_cndmask_b32_e32 v38, v38, v18, vcc
	v_cmp_eq_u32_e32 vcc, 17, v37
	s_nop 1
	v_cndmask_b32_e32 v38, v38, v19, vcc
	v_cmp_eq_u32_e32 vcc, 18, v37
	s_nop 1
	v_cndmask_b32_e32 v38, v38, v20, vcc
	v_cmp_eq_u32_e32 vcc, 19, v37
	s_nop 1
	v_cndmask_b32_e32 v38, v38, v21, vcc
	v_cmp_eq_u32_e32 vcc, 20, v37
	s_nop 1
	v_cndmask_b32_e32 v38, v38, v22, vcc
	v_cmp_eq_u32_e32 vcc, 21, v37
	s_nop 1
	v_cndmask_b32_e32 v38, v38, v23, vcc
	v_cmp_eq_u32_e32 vcc, 22, v37
	s_nop 1
	v_cndmask_b32_e32 v38, v38, v24, vcc
	v_cmp_eq_u32_e32 vcc, 23, v37
	s_nop 1
	v_cndmask_b32_e32 v38, v38, v25, vcc
	v_cmp_eq_u32_e32 vcc, 24, v37
	s_nop 1
	v_cndmask_b32_e32 v38, v38, v26, vcc
	v_cmp_eq_u32_e32 vcc, 25, v37
	s_nop 1
	v_cndmask_b32_e32 v38, v38, v27, vcc
	v_cmp_eq_u32_e32 vcc, 26, v37
	s_nop 1
	v_cndmask_b32_e32 v38, v38, v28, vcc
	v_cmp_eq_u32_e32 vcc, 27, v37
	s_nop 1
	v_cndmask_b32_e32 v38, v38, v29, vcc
	v_cmp_eq_u32_e32 vcc, 28, v37
	s_nop 1
	v_cndmask_b32_e32 v38, v38, v30, vcc
	v_cmp_eq_u32_e32 vcc, 29, v37
	s_nop 1
	v_cndmask_b32_e32 v38, v38, v31, vcc
	v_cmp_eq_u32_e32 vcc, 30, v37
	s_nop 1
	v_cndmask_b32_e32 v38, v38, v32, vcc
	v_cmp_eq_u32_e32 vcc, 31, v37
	s_nop 1
	v_cndmask_b32_e32 v38, v38, v33, vcc
	v_cmp_ngt_f32_e32 vcc, 1.0, v38
	s_and_saveexec_b64 s[2:3], vcc
	s_xor_b64 s[2:3], exec, s[2:3]
	v_lshrrev_b32_e32 v37, 20, v38
	v_add_u32_e32 v37, 0xfffffc10, v37
	s_andn2_saveexec_b64 s[2:3], s[2:3]
	v_mul_f32_e32 v37, 0x41000000, v38
	v_cvt_i32_f32_e32 v37, v37
	s_or_b64 exec, exec, s[2:3]
	v_cndmask_b32_e64 v38, 21, 5, s[0:1]
	v_cmp_eq_u32_e32 vcc, 1, v38
	s_nop 1
	v_cndmask_b32_e32 v39, v2, v3, vcc
	v_cmp_eq_u32_e32 vcc, 2, v38
	s_nop 1
	v_cndmask_b32_e32 v39, v39, v4, vcc
	v_cmp_eq_u32_e32 vcc, 3, v38
	s_nop 1
	v_cndmask_b32_e32 v39, v39, v5, vcc
	v_cmp_eq_u32_e32 vcc, 4, v38
	s_nop 1
	v_cndmask_b32_e32 v39, v39, v6, vcc
	v_cmp_eq_u32_e32 vcc, 5, v38
	s_nop 1
	v_cndmask_b32_e32 v39, v39, v7, vcc
	v_cmp_eq_u32_e32 vcc, 6, v38
	s_nop 1
	v_cndmask_b32_e32 v39, v39, v8, vcc
	v_cmp_eq_u32_e32 vcc, 7, v38
	s_nop 1
	v_cndmask_b32_e32 v39, v39, v9, vcc
	v_cmp_eq_u32_e32 vcc, 8, v38
	s_nop 1
	v_cndmask_b32_e32 v39, v39, v10, vcc
	v_cmp_eq_u32_e32 vcc, 9, v38
	s_nop 1
	v_cndmask_b32_e32 v39, v39, v11, vcc
	v_cmp_eq_u32_e32 vcc, 10, v38
	s_nop 1
	v_cndmask_b32_e32 v39, v39, v12, vcc
	v_cmp_eq_u32_e32 vcc, 11, v38
	s_nop 1
	v_cndmask_b32_e32 v39, v39, v13, vcc
	v_cmp_eq_u32_e32 vcc, 12, v38
	s_nop 1
	v_cndmask_b32_e32 v39, v39, v14, vcc
	v_cmp_eq_u32_e32 vcc, 13, v38
	s_nop 1
	v_cndmask_b32_e32 v39, v39, v15, vcc
	v_cmp_eq_u32_e32 vcc, 14, v38
	s_nop 1
	v_cndmask_b32_e32 v39, v39, v16, vcc
	v_cmp_eq_u32_e32 vcc, 15, v38
	s_nop 1
	v_cndmask_b32_e32 v39, v39, v17, vcc
	v_cmp_eq_u32_e32 vcc, 16, v38
	s_nop 1
	v_cndmask_b32_e32 v39, v39, v18, vcc
	v_cmp_eq_u32_e32 vcc, 17, v38
	s_nop 1
	v_cndmask_b32_e32 v39, v39, v19, vcc
	v_cmp_eq_u32_e32 vcc, 18, v38
	s_nop 1
	v_cndmask_b32_e32 v39, v39, v20, vcc
	v_cmp_eq_u32_e32 vcc, 19, v38
	s_nop 1
	v_cndmask_b32_e32 v39, v39, v21, vcc
	v_cmp_eq_u32_e32 vcc, 20, v38
	s_nop 1
	v_cndmask_b32_e32 v39, v39, v22, vcc
	v_cmp_eq_u32_e32 vcc, 21, v38
	s_nop 1
	v_cndmask_b32_e32 v39, v39, v23, vcc
	v_cmp_eq_u32_e32 vcc, 22, v38
	s_nop 1
	v_cndmask_b32_e32 v39, v39, v24, vcc
	v_cmp_eq_u32_e32 vcc, 23, v38
	s_nop 1
	v_cndmask_b32_e32 v39, v39, v25, vcc
	v_cmp_eq_u32_e32 vcc, 24, v38
	s_nop 1
	v_cndmask_b32_e32 v39, v39, v26, vcc
	v_cmp_eq_u32_e32 vcc, 25, v38
	s_nop 1
	v_cndmask_b32_e32 v39, v39, v27, vcc
	v_cmp_eq_u32_e32 vcc, 26, v38
	s_nop 1
	v_cndmask_b32_e32 v39, v39, v28, vcc
	v_cmp_eq_u32_e32 vcc, 27, v38
	s_nop 1
	v_cndmask_b32_e32 v39, v39, v29, vcc
	v_cmp_eq_u32_e32 vcc, 28, v38
	s_nop 1
	v_cndmask_b32_e32 v39, v39, v30, vcc
	v_cmp_eq_u32_e32 vcc, 29, v38
	s_nop 1
	v_cndmask_b32_e32 v39, v39, v31, vcc
	v_cmp_eq_u32_e32 vcc, 30, v38
	s_nop 1
	v_cndmask_b32_e32 v39, v39, v32, vcc
	v_cmp_eq_u32_e32 vcc, 31, v38
	s_nop 1
	v_cndmask_b32_e32 v39, v39, v33, vcc
	v_cmp_ngt_f32_e32 vcc, 1.0, v39
	s_and_saveexec_b64 s[2:3], vcc
	s_xor_b64 s[2:3], exec, s[2:3]
	v_lshrrev_b32_e32 v38, 20, v39
	v_add_u32_e32 v38, 0xfffffc10, v38
	s_andn2_saveexec_b64 s[2:3], s[2:3]
	v_mul_f32_e32 v38, 0x41000000, v39
	v_cvt_i32_f32_e32 v38, v38
	s_or_b64 exec, exec, s[2:3]
	v_cndmask_b32_e64 v39, 22, 6, s[0:1]
	v_cmp_eq_u32_e32 vcc, 1, v39
	s_nop 1
	v_cndmask_b32_e32 v40, v2, v3, vcc
	v_cmp_eq_u32_e32 vcc, 2, v39
	s_nop 1
	v_cndmask_b32_e32 v40, v40, v4, vcc
	v_cmp_eq_u32_e32 vcc, 3, v39
	s_nop 1
	v_cndmask_b32_e32 v40, v40, v5, vcc
	v_cmp_eq_u32_e32 vcc, 4, v39
	s_nop 1
	v_cndmask_b32_e32 v40, v40, v6, vcc
	v_cmp_eq_u32_e32 vcc, 5, v39
	s_nop 1
	v_cndmask_b32_e32 v40, v40, v7, vcc
	v_cmp_eq_u32_e32 vcc, 6, v39
	s_nop 1
	v_cndmask_b32_e32 v40, v40, v8, vcc
	v_cmp_eq_u32_e32 vcc, 7, v39
	s_nop 1
	v_cndmask_b32_e32 v40, v40, v9, vcc
	v_cmp_eq_u32_e32 vcc, 8, v39
	s_nop 1
	v_cndmask_b32_e32 v40, v40, v10, vcc
	v_cmp_eq_u32_e32 vcc, 9, v39
	s_nop 1
	v_cndmask_b32_e32 v40, v40, v11, vcc
	v_cmp_eq_u32_e32 vcc, 10, v39
	s_nop 1
	v_cndmask_b32_e32 v40, v40, v12, vcc
	v_cmp_eq_u32_e32 vcc, 11, v39
	s_nop 1
	v_cndmask_b32_e32 v40, v40, v13, vcc
	v_cmp_eq_u32_e32 vcc, 12, v39
	s_nop 1
	v_cndmask_b32_e32 v40, v40, v14, vcc
	v_cmp_eq_u32_e32 vcc, 13, v39
	s_nop 1
	v_cndmask_b32_e32 v40, v40, v15, vcc
	v_cmp_eq_u32_e32 vcc, 14, v39
	s_nop 1
	v_cndmask_b32_e32 v40, v40, v16, vcc
	v_cmp_eq_u32_e32 vcc, 15, v39
	s_nop 1
	v_cndmask_b32_e32 v40, v40, v17, vcc
	v_cmp_eq_u32_e32 vcc, 16, v39
	s_nop 1
	v_cndmask_b32_e32 v40, v40, v18, vcc
	v_cmp_eq_u32_e32 vcc, 17, v39
	s_nop 1
	v_cndmask_b32_e32 v40, v40, v19, vcc
	v_cmp_eq_u32_e32 vcc, 18, v39
	s_nop 1
	v_cndmask_b32_e32 v40, v40, v20, vcc
	v_cmp_eq_u32_e32 vcc, 19, v39
	s_nop 1
	v_cndmask_b32_e32 v40, v40, v21, vcc
	v_cmp_eq_u32_e32 vcc, 20, v39
	s_nop 1
	v_cndmask_b32_e32 v40, v40, v22, vcc
	v_cmp_eq_u32_e32 vcc, 21, v39
	s_nop 1
	v_cndmask_b32_e32 v40, v40, v23, vcc
	v_cmp_eq_u32_e32 vcc, 22, v39
	s_nop 1
	v_cndmask_b32_e32 v40, v40, v24, vcc
	v_cmp_eq_u32_e32 vcc, 23, v39
	s_nop 1
	v_cndmask_b32_e32 v40, v40, v25, vcc
	v_cmp_eq_u32_e32 vcc, 24, v39
	s_nop 1
	v_cndmask_b32_e32 v40, v40, v26, vcc
	v_cmp_eq_u32_e32 vcc, 25, v39
	s_nop 1
	v_cndmask_b32_e32 v40, v40, v27, vcc
	v_cmp_eq_u32_e32 vcc, 26, v39
	s_nop 1
	v_cndmask_b32_e32 v40, v40, v28, vcc
	v_cmp_eq_u32_e32 vcc, 27, v39
	s_nop 1
	v_cndmask_b32_e32 v40, v40, v29, vcc
	v_cmp_eq_u32_e32 vcc, 28, v39
	s_nop 1
	v_cndmask_b32_e32 v40, v40, v30, vcc
	v_cmp_eq_u32_e32 vcc, 29, v39
	s_nop 1
	v_cndmask_b32_e32 v40, v40, v31, vcc
	v_cmp_eq_u32_e32 vcc, 30, v39
	s_nop 1
	v_cndmask_b32_e32 v40, v40, v32, vcc
	v_cmp_eq_u32_e32 vcc, 31, v39
	s_nop 1
	v_cndmask_b32_e32 v40, v40, v33, vcc
	v_cmp_ngt_f32_e32 vcc, 1.0, v40
	s_and_saveexec_b64 s[2:3], vcc
	s_xor_b64 s[2:3], exec, s[2:3]
	v_lshrrev_b32_e32 v39, 20, v40
	v_add_u32_e32 v39, 0xfffffc10, v39
	s_andn2_saveexec_b64 s[2:3], s[2:3]
	v_mul_f32_e32 v39, 0x41000000, v40
	v_cvt_i32_f32_e32 v39, v39
	s_or_b64 exec, exec, s[2:3]
	v_cndmask_b32_e64 v40, 23, 7, s[0:1]
	v_cmp_eq_u32_e32 vcc, 1, v40
	s_nop 1
	v_cndmask_b32_e32 v41, v2, v3, vcc
	v_cmp_eq_u32_e32 vcc, 2, v40
	s_nop 1
	v_cndmask_b32_e32 v41, v41, v4, vcc
	v_cmp_eq_u32_e32 vcc, 3, v40
	s_nop 1
	v_cndmask_b32_e32 v41, v41, v5, vcc
	v_cmp_eq_u32_e32 vcc, 4, v40
	s_nop 1
	v_cndmask_b32_e32 v41, v41, v6, vcc
	v_cmp_eq_u32_e32 vcc, 5, v40
	s_nop 1
	v_cndmask_b32_e32 v41, v41, v7, vcc
	v_cmp_eq_u32_e32 vcc, 6, v40
	s_nop 1
	v_cndmask_b32_e32 v41, v41, v8, vcc
	v_cmp_eq_u32_e32 vcc, 7, v40
	s_nop 1
	v_cndmask_b32_e32 v41, v41, v9, vcc
	v_cmp_eq_u32_e32 vcc, 8, v40
	s_nop 1
	v_cndmask_b32_e32 v41, v41, v10, vcc
	v_cmp_eq_u32_e32 vcc, 9, v40
	s_nop 1
	v_cndmask_b32_e32 v41, v41, v11, vcc
	v_cmp_eq_u32_e32 vcc, 10, v40
	s_nop 1
	v_cndmask_b32_e32 v41, v41, v12, vcc
	v_cmp_eq_u32_e32 vcc, 11, v40
	s_nop 1
	v_cndmask_b32_e32 v41, v41, v13, vcc
	v_cmp_eq_u32_e32 vcc, 12, v40
	s_nop 1
	v_cndmask_b32_e32 v41, v41, v14, vcc
	v_cmp_eq_u32_e32 vcc, 13, v40
	s_nop 1
	v_cndmask_b32_e32 v41, v41, v15, vcc
	v_cmp_eq_u32_e32 vcc, 14, v40
	s_nop 1
	v_cndmask_b32_e32 v41, v41, v16, vcc
	v_cmp_eq_u32_e32 vcc, 15, v40
	s_nop 1
	v_cndmask_b32_e32 v41, v41, v17, vcc
	v_cmp_eq_u32_e32 vcc, 16, v40
	s_nop 1
	v_cndmask_b32_e32 v41, v41, v18, vcc
	v_cmp_eq_u32_e32 vcc, 17, v40
	s_nop 1
	v_cndmask_b32_e32 v41, v41, v19, vcc
	v_cmp_eq_u32_e32 vcc, 18, v40
	s_nop 1
	v_cndmask_b32_e32 v41, v41, v20, vcc
	v_cmp_eq_u32_e32 vcc, 19, v40
	s_nop 1
	v_cndmask_b32_e32 v41, v41, v21, vcc
	v_cmp_eq_u32_e32 vcc, 20, v40
	s_nop 1
	v_cndmask_b32_e32 v41, v41, v22, vcc
	v_cmp_eq_u32_e32 vcc, 21, v40
	s_nop 1
	v_cndmask_b32_e32 v41, v41, v23, vcc
	v_cmp_eq_u32_e32 vcc, 22, v40
	s_nop 1
	v_cndmask_b32_e32 v41, v41, v24, vcc
	v_cmp_eq_u32_e32 vcc, 23, v40
	s_nop 1
	v_cndmask_b32_e32 v41, v41, v25, vcc
	v_cmp_eq_u32_e32 vcc, 24, v40
	s_nop 1
	v_cndmask_b32_e32 v41, v41, v26, vcc
	v_cmp_eq_u32_e32 vcc, 25, v40
	s_nop 1
	v_cndmask_b32_e32 v41, v41, v27, vcc
	v_cmp_eq_u32_e32 vcc, 26, v40
	s_nop 1
	v_cndmask_b32_e32 v41, v41, v28, vcc
	v_cmp_eq_u32_e32 vcc, 27, v40
	s_nop 1
	v_cndmask_b32_e32 v41, v41, v29, vcc
	v_cmp_eq_u32_e32 vcc, 28, v40
	s_nop 1
	v_cndmask_b32_e32 v41, v41, v30, vcc
	v_cmp_eq_u32_e32 vcc, 29, v40
	s_nop 1
	v_cndmask_b32_e32 v41, v41, v31, vcc
	v_cmp_eq_u32_e32 vcc, 30, v40
	s_nop 1
	v_cndmask_b32_e32 v41, v41, v32, vcc
	v_cmp_eq_u32_e32 vcc, 31, v40
	s_nop 1
	v_cndmask_b32_e32 v41, v41, v33, vcc
	v_cmp_ngt_f32_e32 vcc, 1.0, v41
	s_and_saveexec_b64 s[2:3], vcc
	s_xor_b64 s[2:3], exec, s[2:3]
	v_lshrrev_b32_e32 v40, 20, v41
	v_add_u32_e32 v40, 0xfffffc10, v40
	s_andn2_saveexec_b64 s[2:3], s[2:3]
	v_mul_f32_e32 v40, 0x41000000, v41
	v_cvt_i32_f32_e32 v40, v40
	s_or_b64 exec, exec, s[2:3]
	v_cndmask_b32_e64 v41, 24, 8, s[0:1]
	v_cmp_eq_u32_e32 vcc, 1, v41
	s_nop 1
	v_cndmask_b32_e32 v42, v2, v3, vcc
	v_cmp_eq_u32_e32 vcc, 2, v41
	s_nop 1
	v_cndmask_b32_e32 v42, v42, v4, vcc
	v_cmp_eq_u32_e32 vcc, 3, v41
	s_nop 1
	v_cndmask_b32_e32 v42, v42, v5, vcc
	v_cmp_eq_u32_e32 vcc, 4, v41
	s_nop 1
	v_cndmask_b32_e32 v42, v42, v6, vcc
	v_cmp_eq_u32_e32 vcc, 5, v41
	s_nop 1
	v_cndmask_b32_e32 v42, v42, v7, vcc
	v_cmp_eq_u32_e32 vcc, 6, v41
	s_nop 1
	v_cndmask_b32_e32 v42, v42, v8, vcc
	v_cmp_eq_u32_e32 vcc, 7, v41
	s_nop 1
	v_cndmask_b32_e32 v42, v42, v9, vcc
	v_cmp_eq_u32_e32 vcc, 8, v41
	s_nop 1
	v_cndmask_b32_e32 v42, v42, v10, vcc
	v_cmp_eq_u32_e32 vcc, 9, v41
	s_nop 1
	v_cndmask_b32_e32 v42, v42, v11, vcc
	v_cmp_eq_u32_e32 vcc, 10, v41
	s_nop 1
	v_cndmask_b32_e32 v42, v42, v12, vcc
	v_cmp_eq_u32_e32 vcc, 11, v41
	s_nop 1
	v_cndmask_b32_e32 v42, v42, v13, vcc
	v_cmp_eq_u32_e32 vcc, 12, v41
	s_nop 1
	v_cndmask_b32_e32 v42, v42, v14, vcc
	v_cmp_eq_u32_e32 vcc, 13, v41
	s_nop 1
	v_cndmask_b32_e32 v42, v42, v15, vcc
	v_cmp_eq_u32_e32 vcc, 14, v41
	s_nop 1
	v_cndmask_b32_e32 v42, v42, v16, vcc
	v_cmp_eq_u32_e32 vcc, 15, v41
	s_nop 1
	v_cndmask_b32_e32 v42, v42, v17, vcc
	v_cmp_eq_u32_e32 vcc, 16, v41
	s_nop 1
	v_cndmask_b32_e32 v42, v42, v18, vcc
	v_cmp_eq_u32_e32 vcc, 17, v41
	s_nop 1
	v_cndmask_b32_e32 v42, v42, v19, vcc
	v_cmp_eq_u32_e32 vcc, 18, v41
	s_nop 1
	v_cndmask_b32_e32 v42, v42, v20, vcc
	v_cmp_eq_u32_e32 vcc, 19, v41
	s_nop 1
	v_cndmask_b32_e32 v42, v42, v21, vcc
	v_cmp_eq_u32_e32 vcc, 20, v41
	s_nop 1
	v_cndmask_b32_e32 v42, v42, v22, vcc
	v_cmp_eq_u32_e32 vcc, 21, v41
	s_nop 1
	v_cndmask_b32_e32 v42, v42, v23, vcc
	v_cmp_eq_u32_e32 vcc, 22, v41
	s_nop 1
	v_cndmask_b32_e32 v42, v42, v24, vcc
	v_cmp_eq_u32_e32 vcc, 23, v41
	s_nop 1
	v_cndmask_b32_e32 v42, v42, v25, vcc
	v_cmp_eq_u32_e32 vcc, 24, v41
	s_nop 1
	v_cndmask_b32_e32 v42, v42, v26, vcc
	v_cmp_eq_u32_e32 vcc, 25, v41
	s_nop 1
	v_cndmask_b32_e32 v42, v42, v27, vcc
	v_cmp_eq_u32_e32 vcc, 26, v41
	s_nop 1
	v_cndmask_b32_e32 v42, v42, v28, vcc
	v_cmp_eq_u32_e32 vcc, 27, v41
	s_nop 1
	v_cndmask_b32_e32 v42, v42, v29, vcc
	v_cmp_eq_u32_e32 vcc, 28, v41
	s_nop 1
	v_cndmask_b32_e32 v42, v42, v30, vcc
	v_cmp_eq_u32_e32 vcc, 29, v41
	s_nop 1
	v_cndmask_b32_e32 v42, v42, v31, vcc
	v_cmp_eq_u32_e32 vcc, 30, v41
	s_nop 1
	v_cndmask_b32_e32 v42, v42, v32, vcc
	v_cmp_eq_u32_e32 vcc, 31, v41
	s_nop 1
	v_cndmask_b32_e32 v42, v42, v33, vcc
	v_cmp_ngt_f32_e32 vcc, 1.0, v42
	s_and_saveexec_b64 s[2:3], vcc
	s_xor_b64 s[2:3], exec, s[2:3]
	v_lshrrev_b32_e32 v41, 20, v42
	v_add_u32_e32 v41, 0xfffffc10, v41
	s_andn2_saveexec_b64 s[2:3], s[2:3]
	v_mul_f32_e32 v41, 0x41000000, v42
	v_cvt_i32_f32_e32 v41, v41
	s_or_b64 exec, exec, s[2:3]
	v_cndmask_b32_e64 v42, 25, 9, s[0:1]
	v_cmp_eq_u32_e32 vcc, 1, v42
	s_nop 1
	v_cndmask_b32_e32 v43, v2, v3, vcc
	v_cmp_eq_u32_e32 vcc, 2, v42
	s_nop 1
	v_cndmask_b32_e32 v43, v43, v4, vcc
	v_cmp_eq_u32_e32 vcc, 3, v42
	s_nop 1
	v_cndmask_b32_e32 v43, v43, v5, vcc
	v_cmp_eq_u32_e32 vcc, 4, v42
	s_nop 1
	v_cndmask_b32_e32 v43, v43, v6, vcc
	v_cmp_eq_u32_e32 vcc, 5, v42
	s_nop 1
	v_cndmask_b32_e32 v43, v43, v7, vcc
	v_cmp_eq_u32_e32 vcc, 6, v42
	s_nop 1
	v_cndmask_b32_e32 v43, v43, v8, vcc
	v_cmp_eq_u32_e32 vcc, 7, v42
	s_nop 1
	v_cndmask_b32_e32 v43, v43, v9, vcc
	v_cmp_eq_u32_e32 vcc, 8, v42
	s_nop 1
	v_cndmask_b32_e32 v43, v43, v10, vcc
	v_cmp_eq_u32_e32 vcc, 9, v42
	s_nop 1
	v_cndmask_b32_e32 v43, v43, v11, vcc
	v_cmp_eq_u32_e32 vcc, 10, v42
	s_nop 1
	v_cndmask_b32_e32 v43, v43, v12, vcc
	v_cmp_eq_u32_e32 vcc, 11, v42
	s_nop 1
	v_cndmask_b32_e32 v43, v43, v13, vcc
	v_cmp_eq_u32_e32 vcc, 12, v42
	s_nop 1
	v_cndmask_b32_e32 v43, v43, v14, vcc
	v_cmp_eq_u32_e32 vcc, 13, v42
	s_nop 1
	v_cndmask_b32_e32 v43, v43, v15, vcc
	v_cmp_eq_u32_e32 vcc, 14, v42
	s_nop 1
	v_cndmask_b32_e32 v43, v43, v16, vcc
	v_cmp_eq_u32_e32 vcc, 15, v42
	s_nop 1
	v_cndmask_b32_e32 v43, v43, v17, vcc
	v_cmp_eq_u32_e32 vcc, 16, v42
	s_nop 1
	v_cndmask_b32_e32 v43, v43, v18, vcc
	v_cmp_eq_u32_e32 vcc, 17, v42
	s_nop 1
	v_cndmask_b32_e32 v43, v43, v19, vcc
	v_cmp_eq_u32_e32 vcc, 18, v42
	s_nop 1
	v_cndmask_b32_e32 v43, v43, v20, vcc
	v_cmp_eq_u32_e32 vcc, 19, v42
	s_nop 1
	v_cndmask_b32_e32 v43, v43, v21, vcc
	v_cmp_eq_u32_e32 vcc, 20, v42
	s_nop 1
	v_cndmask_b32_e32 v43, v43, v22, vcc
	v_cmp_eq_u32_e32 vcc, 21, v42
	s_nop 1
	v_cndmask_b32_e32 v43, v43, v23, vcc
	v_cmp_eq_u32_e32 vcc, 22, v42
	s_nop 1
	v_cndmask_b32_e32 v43, v43, v24, vcc
	v_cmp_eq_u32_e32 vcc, 23, v42
	s_nop 1
	v_cndmask_b32_e32 v43, v43, v25, vcc
	v_cmp_eq_u32_e32 vcc, 24, v42
	s_nop 1
	v_cndmask_b32_e32 v43, v43, v26, vcc
	v_cmp_eq_u32_e32 vcc, 25, v42
	s_nop 1
	v_cndmask_b32_e32 v43, v43, v27, vcc
	v_cmp_eq_u32_e32 vcc, 26, v42
	s_nop 1
	v_cndmask_b32_e32 v43, v43, v28, vcc
	v_cmp_eq_u32_e32 vcc, 27, v42
	s_nop 1
	v_cndmask_b32_e32 v43, v43, v29, vcc
	v_cmp_eq_u32_e32 vcc, 28, v42
	s_nop 1
	v_cndmask_b32_e32 v43, v43, v30, vcc
	v_cmp_eq_u32_e32 vcc, 29, v42
	s_nop 1
	v_cndmask_b32_e32 v43, v43, v31, vcc
	v_cmp_eq_u32_e32 vcc, 30, v42
	s_nop 1
	v_cndmask_b32_e32 v43, v43, v32, vcc
	v_cmp_eq_u32_e32 vcc, 31, v42
	s_nop 1
	v_cndmask_b32_e32 v43, v43, v33, vcc
	v_cmp_ngt_f32_e32 vcc, 1.0, v43
	s_and_saveexec_b64 s[2:3], vcc
	s_xor_b64 s[2:3], exec, s[2:3]
	v_lshrrev_b32_e32 v42, 20, v43
	v_add_u32_e32 v42, 0xfffffc10, v42
	s_andn2_saveexec_b64 s[2:3], s[2:3]
	v_mul_f32_e32 v42, 0x41000000, v43
	v_cvt_i32_f32_e32 v42, v42
	s_or_b64 exec, exec, s[2:3]
	v_cndmask_b32_e64 v43, 26, 10, s[0:1]
	v_cmp_eq_u32_e32 vcc, 1, v43
	s_nop 1
	v_cndmask_b32_e32 v44, v2, v3, vcc
	v_cmp_eq_u32_e32 vcc, 2, v43
	s_nop 1
	v_cndmask_b32_e32 v44, v44, v4, vcc
	v_cmp_eq_u32_e32 vcc, 3, v43
	s_nop 1
	v_cndmask_b32_e32 v44, v44, v5, vcc
	v_cmp_eq_u32_e32 vcc, 4, v43
	s_nop 1
	v_cndmask_b32_e32 v44, v44, v6, vcc
	v_cmp_eq_u32_e32 vcc, 5, v43
	s_nop 1
	v_cndmask_b32_e32 v44, v44, v7, vcc
	v_cmp_eq_u32_e32 vcc, 6, v43
	s_nop 1
	v_cndmask_b32_e32 v44, v44, v8, vcc
	v_cmp_eq_u32_e32 vcc, 7, v43
	s_nop 1
	v_cndmask_b32_e32 v44, v44, v9, vcc
	v_cmp_eq_u32_e32 vcc, 8, v43
	s_nop 1
	v_cndmask_b32_e32 v44, v44, v10, vcc
	v_cmp_eq_u32_e32 vcc, 9, v43
	s_nop 1
	v_cndmask_b32_e32 v44, v44, v11, vcc
	v_cmp_eq_u32_e32 vcc, 10, v43
	s_nop 1
	v_cndmask_b32_e32 v44, v44, v12, vcc
	v_cmp_eq_u32_e32 vcc, 11, v43
	s_nop 1
	v_cndmask_b32_e32 v44, v44, v13, vcc
	v_cmp_eq_u32_e32 vcc, 12, v43
	s_nop 1
	v_cndmask_b32_e32 v44, v44, v14, vcc
	v_cmp_eq_u32_e32 vcc, 13, v43
	s_nop 1
	v_cndmask_b32_e32 v44, v44, v15, vcc
	v_cmp_eq_u32_e32 vcc, 14, v43
	s_nop 1
	v_cndmask_b32_e32 v44, v44, v16, vcc
	v_cmp_eq_u32_e32 vcc, 15, v43
	s_nop 1
	v_cndmask_b32_e32 v44, v44, v17, vcc
	v_cmp_eq_u32_e32 vcc, 16, v43
	s_nop 1
	v_cndmask_b32_e32 v44, v44, v18, vcc
	v_cmp_eq_u32_e32 vcc, 17, v43
	s_nop 1
	v_cndmask_b32_e32 v44, v44, v19, vcc
	v_cmp_eq_u32_e32 vcc, 18, v43
	s_nop 1
	v_cndmask_b32_e32 v44, v44, v20, vcc
	v_cmp_eq_u32_e32 vcc, 19, v43
	s_nop 1
	v_cndmask_b32_e32 v44, v44, v21, vcc
	v_cmp_eq_u32_e32 vcc, 20, v43
	s_nop 1
	v_cndmask_b32_e32 v44, v44, v22, vcc
	v_cmp_eq_u32_e32 vcc, 21, v43
	s_nop 1
	v_cndmask_b32_e32 v44, v44, v23, vcc
	v_cmp_eq_u32_e32 vcc, 22, v43
	s_nop 1
	v_cndmask_b32_e32 v44, v44, v24, vcc
	v_cmp_eq_u32_e32 vcc, 23, v43
	s_nop 1
	v_cndmask_b32_e32 v44, v44, v25, vcc
	v_cmp_eq_u32_e32 vcc, 24, v43
	s_nop 1
	v_cndmask_b32_e32 v44, v44, v26, vcc
	v_cmp_eq_u32_e32 vcc, 25, v43
	s_nop 1
	v_cndmask_b32_e32 v44, v44, v27, vcc
	v_cmp_eq_u32_e32 vcc, 26, v43
	s_nop 1
	v_cndmask_b32_e32 v44, v44, v28, vcc
	v_cmp_eq_u32_e32 vcc, 27, v43
	s_nop 1
	v_cndmask_b32_e32 v44, v44, v29, vcc
	v_cmp_eq_u32_e32 vcc, 28, v43
	s_nop 1
	v_cndmask_b32_e32 v44, v44, v30, vcc
	v_cmp_eq_u32_e32 vcc, 29, v43
	s_nop 1
	v_cndmask_b32_e32 v44, v44, v31, vcc
	v_cmp_eq_u32_e32 vcc, 30, v43
	s_nop 1
	v_cndmask_b32_e32 v44, v44, v32, vcc
	v_cmp_eq_u32_e32 vcc, 31, v43
	s_nop 1
	v_cndmask_b32_e32 v44, v44, v33, vcc
	v_cmp_ngt_f32_e32 vcc, 1.0, v44
	s_and_saveexec_b64 s[2:3], vcc
	s_xor_b64 s[2:3], exec, s[2:3]
	v_lshrrev_b32_e32 v43, 20, v44
	v_add_u32_e32 v43, 0xfffffc10, v43
	s_andn2_saveexec_b64 s[2:3], s[2:3]
	v_mul_f32_e32 v43, 0x41000000, v44
	v_cvt_i32_f32_e32 v43, v43
	s_or_b64 exec, exec, s[2:3]
	v_cndmask_b32_e64 v44, 27, 11, s[0:1]
	v_cmp_eq_u32_e32 vcc, 1, v44
	s_nop 1
	v_cndmask_b32_e32 v45, v2, v3, vcc
	v_cmp_eq_u32_e32 vcc, 2, v44
	s_nop 1
	v_cndmask_b32_e32 v45, v45, v4, vcc
	v_cmp_eq_u32_e32 vcc, 3, v44
	s_nop 1
	v_cndmask_b32_e32 v45, v45, v5, vcc
	v_cmp_eq_u32_e32 vcc, 4, v44
	s_nop 1
	v_cndmask_b32_e32 v45, v45, v6, vcc
	v_cmp_eq_u32_e32 vcc, 5, v44
	s_nop 1
	v_cndmask_b32_e32 v45, v45, v7, vcc
	v_cmp_eq_u32_e32 vcc, 6, v44
	s_nop 1
	v_cndmask_b32_e32 v45, v45, v8, vcc
	v_cmp_eq_u32_e32 vcc, 7, v44
	s_nop 1
	v_cndmask_b32_e32 v45, v45, v9, vcc
	v_cmp_eq_u32_e32 vcc, 8, v44
	s_nop 1
	v_cndmask_b32_e32 v45, v45, v10, vcc
	v_cmp_eq_u32_e32 vcc, 9, v44
	s_nop 1
	v_cndmask_b32_e32 v45, v45, v11, vcc
	v_cmp_eq_u32_e32 vcc, 10, v44
	s_nop 1
	v_cndmask_b32_e32 v45, v45, v12, vcc
	v_cmp_eq_u32_e32 vcc, 11, v44
	s_nop 1
	v_cndmask_b32_e32 v45, v45, v13, vcc
	v_cmp_eq_u32_e32 vcc, 12, v44
	s_nop 1
	v_cndmask_b32_e32 v45, v45, v14, vcc
	v_cmp_eq_u32_e32 vcc, 13, v44
	s_nop 1
	v_cndmask_b32_e32 v45, v45, v15, vcc
	v_cmp_eq_u32_e32 vcc, 14, v44
	s_nop 1
	v_cndmask_b32_e32 v45, v45, v16, vcc
	v_cmp_eq_u32_e32 vcc, 15, v44
	s_nop 1
	v_cndmask_b32_e32 v45, v45, v17, vcc
	v_cmp_eq_u32_e32 vcc, 16, v44
	s_nop 1
	v_cndmask_b32_e32 v45, v45, v18, vcc
	v_cmp_eq_u32_e32 vcc, 17, v44
	s_nop 1
	v_cndmask_b32_e32 v45, v45, v19, vcc
	v_cmp_eq_u32_e32 vcc, 18, v44
	s_nop 1
	v_cndmask_b32_e32 v45, v45, v20, vcc
	v_cmp_eq_u32_e32 vcc, 19, v44
	s_nop 1
	v_cndmask_b32_e32 v45, v45, v21, vcc
	v_cmp_eq_u32_e32 vcc, 20, v44
	s_nop 1
	v_cndmask_b32_e32 v45, v45, v22, vcc
	v_cmp_eq_u32_e32 vcc, 21, v44
	s_nop 1
	v_cndmask_b32_e32 v45, v45, v23, vcc
	v_cmp_eq_u32_e32 vcc, 22, v44
	s_nop 1
	v_cndmask_b32_e32 v45, v45, v24, vcc
	v_cmp_eq_u32_e32 vcc, 23, v44
	s_nop 1
	v_cndmask_b32_e32 v45, v45, v25, vcc
	v_cmp_eq_u32_e32 vcc, 24, v44
	s_nop 1
	v_cndmask_b32_e32 v45, v45, v26, vcc
	v_cmp_eq_u32_e32 vcc, 25, v44
	s_nop 1
	v_cndmask_b32_e32 v45, v45, v27, vcc
	v_cmp_eq_u32_e32 vcc, 26, v44
	s_nop 1
	v_cndmask_b32_e32 v45, v45, v28, vcc
	v_cmp_eq_u32_e32 vcc, 27, v44
	s_nop 1
	v_cndmask_b32_e32 v45, v45, v29, vcc
	v_cmp_eq_u32_e32 vcc, 28, v44
	s_nop 1
	v_cndmask_b32_e32 v45, v45, v30, vcc
	v_cmp_eq_u32_e32 vcc, 29, v44
	s_nop 1
	v_cndmask_b32_e32 v45, v45, v31, vcc
	v_cmp_eq_u32_e32 vcc, 30, v44
	s_nop 1
	v_cndmask_b32_e32 v45, v45, v32, vcc
	v_cmp_eq_u32_e32 vcc, 31, v44
	s_nop 1
	v_cndmask_b32_e32 v45, v45, v33, vcc
	v_cmp_ngt_f32_e32 vcc, 1.0, v45
	s_and_saveexec_b64 s[2:3], vcc
	s_xor_b64 s[2:3], exec, s[2:3]
	v_lshrrev_b32_e32 v44, 20, v45
	v_add_u32_e32 v44, 0xfffffc10, v44
	s_andn2_saveexec_b64 s[2:3], s[2:3]
	v_mul_f32_e32 v44, 0x41000000, v45
	v_cvt_i32_f32_e32 v44, v44
	s_or_b64 exec, exec, s[2:3]
	v_cndmask_b32_e64 v45, 28, 12, s[0:1]
	v_cmp_eq_u32_e32 vcc, 1, v45
	s_nop 1
	v_cndmask_b32_e32 v46, v2, v3, vcc
	v_cmp_eq_u32_e32 vcc, 2, v45
	s_nop 1
	v_cndmask_b32_e32 v46, v46, v4, vcc
	v_cmp_eq_u32_e32 vcc, 3, v45
	s_nop 1
	v_cndmask_b32_e32 v46, v46, v5, vcc
	v_cmp_eq_u32_e32 vcc, 4, v45
	s_nop 1
	v_cndmask_b32_e32 v46, v46, v6, vcc
	v_cmp_eq_u32_e32 vcc, 5, v45
	s_nop 1
	v_cndmask_b32_e32 v46, v46, v7, vcc
	v_cmp_eq_u32_e32 vcc, 6, v45
	s_nop 1
	v_cndmask_b32_e32 v46, v46, v8, vcc
	v_cmp_eq_u32_e32 vcc, 7, v45
	s_nop 1
	v_cndmask_b32_e32 v46, v46, v9, vcc
	v_cmp_eq_u32_e32 vcc, 8, v45
	s_nop 1
	v_cndmask_b32_e32 v46, v46, v10, vcc
	v_cmp_eq_u32_e32 vcc, 9, v45
	s_nop 1
	v_cndmask_b32_e32 v46, v46, v11, vcc
	v_cmp_eq_u32_e32 vcc, 10, v45
	s_nop 1
	v_cndmask_b32_e32 v46, v46, v12, vcc
	v_cmp_eq_u32_e32 vcc, 11, v45
	s_nop 1
	v_cndmask_b32_e32 v46, v46, v13, vcc
	v_cmp_eq_u32_e32 vcc, 12, v45
	s_nop 1
	v_cndmask_b32_e32 v46, v46, v14, vcc
	v_cmp_eq_u32_e32 vcc, 13, v45
	s_nop 1
	v_cndmask_b32_e32 v46, v46, v15, vcc
	v_cmp_eq_u32_e32 vcc, 14, v45
	s_nop 1
	v_cndmask_b32_e32 v46, v46, v16, vcc
	v_cmp_eq_u32_e32 vcc, 15, v45
	s_nop 1
	v_cndmask_b32_e32 v46, v46, v17, vcc
	v_cmp_eq_u32_e32 vcc, 16, v45
	s_nop 1
	v_cndmask_b32_e32 v46, v46, v18, vcc
	v_cmp_eq_u32_e32 vcc, 17, v45
	s_nop 1
	v_cndmask_b32_e32 v46, v46, v19, vcc
	v_cmp_eq_u32_e32 vcc, 18, v45
	s_nop 1
	v_cndmask_b32_e32 v46, v46, v20, vcc
	v_cmp_eq_u32_e32 vcc, 19, v45
	s_nop 1
	v_cndmask_b32_e32 v46, v46, v21, vcc
	v_cmp_eq_u32_e32 vcc, 20, v45
	s_nop 1
	v_cndmask_b32_e32 v46, v46, v22, vcc
	v_cmp_eq_u32_e32 vcc, 21, v45
	s_nop 1
	v_cndmask_b32_e32 v46, v46, v23, vcc
	v_cmp_eq_u32_e32 vcc, 22, v45
	s_nop 1
	v_cndmask_b32_e32 v46, v46, v24, vcc
	v_cmp_eq_u32_e32 vcc, 23, v45
	s_nop 1
	v_cndmask_b32_e32 v46, v46, v25, vcc
	v_cmp_eq_u32_e32 vcc, 24, v45
	s_nop 1
	v_cndmask_b32_e32 v46, v46, v26, vcc
	v_cmp_eq_u32_e32 vcc, 25, v45
	s_nop 1
	v_cndmask_b32_e32 v46, v46, v27, vcc
	v_cmp_eq_u32_e32 vcc, 26, v45
	s_nop 1
	v_cndmask_b32_e32 v46, v46, v28, vcc
	v_cmp_eq_u32_e32 vcc, 27, v45
	s_nop 1
	v_cndmask_b32_e32 v46, v46, v29, vcc
	v_cmp_eq_u32_e32 vcc, 28, v45
	s_nop 1
	v_cndmask_b32_e32 v46, v46, v30, vcc
	v_cmp_eq_u32_e32 vcc, 29, v45
	s_nop 1
	v_cndmask_b32_e32 v46, v46, v31, vcc
	v_cmp_eq_u32_e32 vcc, 30, v45
	s_nop 1
	v_cndmask_b32_e32 v46, v46, v32, vcc
	v_cmp_eq_u32_e32 vcc, 31, v45
	s_nop 1
	v_cndmask_b32_e32 v46, v46, v33, vcc
	v_cmp_ngt_f32_e32 vcc, 1.0, v46
	s_and_saveexec_b64 s[2:3], vcc
	s_xor_b64 s[2:3], exec, s[2:3]
	v_lshrrev_b32_e32 v45, 20, v46
	v_add_u32_e32 v45, 0xfffffc10, v45
	s_andn2_saveexec_b64 s[2:3], s[2:3]
	v_mul_f32_e32 v45, 0x41000000, v46
	v_cvt_i32_f32_e32 v45, v45
	s_or_b64 exec, exec, s[2:3]
	v_cndmask_b32_e64 v46, 29, 13, s[0:1]
	v_cmp_eq_u32_e32 vcc, 1, v46
	s_nop 1
	v_cndmask_b32_e32 v47, v2, v3, vcc
	v_cmp_eq_u32_e32 vcc, 2, v46
	s_nop 1
	v_cndmask_b32_e32 v47, v47, v4, vcc
	v_cmp_eq_u32_e32 vcc, 3, v46
	s_nop 1
	v_cndmask_b32_e32 v47, v47, v5, vcc
	v_cmp_eq_u32_e32 vcc, 4, v46
	s_nop 1
	v_cndmask_b32_e32 v47, v47, v6, vcc
	v_cmp_eq_u32_e32 vcc, 5, v46
	s_nop 1
	v_cndmask_b32_e32 v47, v47, v7, vcc
	v_cmp_eq_u32_e32 vcc, 6, v46
	s_nop 1
	v_cndmask_b32_e32 v47, v47, v8, vcc
	v_cmp_eq_u32_e32 vcc, 7, v46
	s_nop 1
	v_cndmask_b32_e32 v47, v47, v9, vcc
	v_cmp_eq_u32_e32 vcc, 8, v46
	s_nop 1
	v_cndmask_b32_e32 v47, v47, v10, vcc
	v_cmp_eq_u32_e32 vcc, 9, v46
	s_nop 1
	v_cndmask_b32_e32 v47, v47, v11, vcc
	v_cmp_eq_u32_e32 vcc, 10, v46
	s_nop 1
	v_cndmask_b32_e32 v47, v47, v12, vcc
	v_cmp_eq_u32_e32 vcc, 11, v46
	s_nop 1
	v_cndmask_b32_e32 v47, v47, v13, vcc
	v_cmp_eq_u32_e32 vcc, 12, v46
	s_nop 1
	v_cndmask_b32_e32 v47, v47, v14, vcc
	v_cmp_eq_u32_e32 vcc, 13, v46
	s_nop 1
	v_cndmask_b32_e32 v47, v47, v15, vcc
	v_cmp_eq_u32_e32 vcc, 14, v46
	s_nop 1
	v_cndmask_b32_e32 v47, v47, v16, vcc
	v_cmp_eq_u32_e32 vcc, 15, v46
	s_nop 1
	v_cndmask_b32_e32 v47, v47, v17, vcc
	v_cmp_eq_u32_e32 vcc, 16, v46
	s_nop 1
	v_cndmask_b32_e32 v47, v47, v18, vcc
	v_cmp_eq_u32_e32 vcc, 17, v46
	s_nop 1
	v_cndmask_b32_e32 v47, v47, v19, vcc
	v_cmp_eq_u32_e32 vcc, 18, v46
	s_nop 1
	v_cndmask_b32_e32 v47, v47, v20, vcc
	v_cmp_eq_u32_e32 vcc, 19, v46
	s_nop 1
	v_cndmask_b32_e32 v47, v47, v21, vcc
	v_cmp_eq_u32_e32 vcc, 20, v46
	s_nop 1
	v_cndmask_b32_e32 v47, v47, v22, vcc
	v_cmp_eq_u32_e32 vcc, 21, v46
	s_nop 1
	v_cndmask_b32_e32 v47, v47, v23, vcc
	v_cmp_eq_u32_e32 vcc, 22, v46
	s_nop 1
	v_cndmask_b32_e32 v47, v47, v24, vcc
	v_cmp_eq_u32_e32 vcc, 23, v46
	s_nop 1
	v_cndmask_b32_e32 v47, v47, v25, vcc
	v_cmp_eq_u32_e32 vcc, 24, v46
	s_nop 1
	v_cndmask_b32_e32 v47, v47, v26, vcc
	v_cmp_eq_u32_e32 vcc, 25, v46
	s_nop 1
	v_cndmask_b32_e32 v47, v47, v27, vcc
	v_cmp_eq_u32_e32 vcc, 26, v46
	s_nop 1
	v_cndmask_b32_e32 v47, v47, v28, vcc
	v_cmp_eq_u32_e32 vcc, 27, v46
	s_nop 1
	v_cndmask_b32_e32 v47, v47, v29, vcc
	v_cmp_eq_u32_e32 vcc, 28, v46
	s_nop 1
	v_cndmask_b32_e32 v47, v47, v30, vcc
	v_cmp_eq_u32_e32 vcc, 29, v46
	s_nop 1
	v_cndmask_b32_e32 v47, v47, v31, vcc
	v_cmp_eq_u32_e32 vcc, 30, v46
	s_nop 1
	v_cndmask_b32_e32 v47, v47, v32, vcc
	v_cmp_eq_u32_e32 vcc, 31, v46
	s_nop 1
	v_cndmask_b32_e32 v47, v47, v33, vcc
	v_cmp_ngt_f32_e32 vcc, 1.0, v47
	s_and_saveexec_b64 s[2:3], vcc
	s_xor_b64 s[2:3], exec, s[2:3]
	v_lshrrev_b32_e32 v46, 20, v47
	v_add_u32_e32 v46, 0xfffffc10, v46
	s_andn2_saveexec_b64 s[2:3], s[2:3]
	v_mul_f32_e32 v46, 0x41000000, v47
	v_cvt_i32_f32_e32 v46, v46
	s_or_b64 exec, exec, s[2:3]
	v_cndmask_b32_e64 v47, 30, 14, s[0:1]
	v_cmp_eq_u32_e32 vcc, 1, v47
	s_nop 1
	v_cndmask_b32_e32 v48, v2, v3, vcc
	v_cmp_eq_u32_e32 vcc, 2, v47
	s_nop 1
	v_cndmask_b32_e32 v48, v48, v4, vcc
	v_cmp_eq_u32_e32 vcc, 3, v47
	s_nop 1
	v_cndmask_b32_e32 v48, v48, v5, vcc
	v_cmp_eq_u32_e32 vcc, 4, v47
	s_nop 1
	v_cndmask_b32_e32 v48, v48, v6, vcc
	v_cmp_eq_u32_e32 vcc, 5, v47
	s_nop 1
	v_cndmask_b32_e32 v48, v48, v7, vcc
	v_cmp_eq_u32_e32 vcc, 6, v47
	s_nop 1
	v_cndmask_b32_e32 v48, v48, v8, vcc
	v_cmp_eq_u32_e32 vcc, 7, v47
	s_nop 1
	v_cndmask_b32_e32 v48, v48, v9, vcc
	v_cmp_eq_u32_e32 vcc, 8, v47
	s_nop 1
	v_cndmask_b32_e32 v48, v48, v10, vcc
	v_cmp_eq_u32_e32 vcc, 9, v47
	s_nop 1
	v_cndmask_b32_e32 v48, v48, v11, vcc
	v_cmp_eq_u32_e32 vcc, 10, v47
	s_nop 1
	v_cndmask_b32_e32 v48, v48, v12, vcc
	v_cmp_eq_u32_e32 vcc, 11, v47
	s_nop 1
	v_cndmask_b32_e32 v48, v48, v13, vcc
	v_cmp_eq_u32_e32 vcc, 12, v47
	s_nop 1
	v_cndmask_b32_e32 v48, v48, v14, vcc
	v_cmp_eq_u32_e32 vcc, 13, v47
	s_nop 1
	v_cndmask_b32_e32 v48, v48, v15, vcc
	v_cmp_eq_u32_e32 vcc, 14, v47
	s_nop 1
	v_cndmask_b32_e32 v48, v48, v16, vcc
	v_cmp_eq_u32_e32 vcc, 15, v47
	s_nop 1
	v_cndmask_b32_e32 v48, v48, v17, vcc
	v_cmp_eq_u32_e32 vcc, 16, v47
	s_nop 1
	v_cndmask_b32_e32 v48, v48, v18, vcc
	v_cmp_eq_u32_e32 vcc, 17, v47
	s_nop 1
	v_cndmask_b32_e32 v48, v48, v19, vcc
	v_cmp_eq_u32_e32 vcc, 18, v47
	s_nop 1
	v_cndmask_b32_e32 v48, v48, v20, vcc
	v_cmp_eq_u32_e32 vcc, 19, v47
	s_nop 1
	v_cndmask_b32_e32 v48, v48, v21, vcc
	v_cmp_eq_u32_e32 vcc, 20, v47
	s_nop 1
	v_cndmask_b32_e32 v48, v48, v22, vcc
	v_cmp_eq_u32_e32 vcc, 21, v47
	s_nop 1
	v_cndmask_b32_e32 v48, v48, v23, vcc
	v_cmp_eq_u32_e32 vcc, 22, v47
	s_nop 1
	v_cndmask_b32_e32 v48, v48, v24, vcc
	v_cmp_eq_u32_e32 vcc, 23, v47
	s_nop 1
	v_cndmask_b32_e32 v48, v48, v25, vcc
	v_cmp_eq_u32_e32 vcc, 24, v47
	s_nop 1
	v_cndmask_b32_e32 v48, v48, v26, vcc
	v_cmp_eq_u32_e32 vcc, 25, v47
	s_nop 1
	v_cndmask_b32_e32 v48, v48, v27, vcc
	v_cmp_eq_u32_e32 vcc, 26, v47
	s_nop 1
	v_cndmask_b32_e32 v48, v48, v28, vcc
	v_cmp_eq_u32_e32 vcc, 27, v47
	s_nop 1
	v_cndmask_b32_e32 v48, v48, v29, vcc
	v_cmp_eq_u32_e32 vcc, 28, v47
	s_nop 1
	v_cndmask_b32_e32 v48, v48, v30, vcc
	v_cmp_eq_u32_e32 vcc, 29, v47
	s_nop 1
	v_cndmask_b32_e32 v48, v48, v31, vcc
	v_cmp_eq_u32_e32 vcc, 30, v47
	s_nop 1
	v_cndmask_b32_e32 v48, v48, v32, vcc
	v_cmp_eq_u32_e32 vcc, 31, v47
	s_nop 1
	v_cndmask_b32_e32 v48, v48, v33, vcc
	v_cmp_ngt_f32_e32 vcc, 1.0, v48
	s_and_saveexec_b64 s[2:3], vcc
	s_xor_b64 s[2:3], exec, s[2:3]
	v_lshrrev_b32_e32 v47, 20, v48
	v_add_u32_e32 v47, 0xfffffc10, v47
	s_andn2_saveexec_b64 s[2:3], s[2:3]
	v_mul_f32_e32 v47, 0x41000000, v48
	v_cvt_i32_f32_e32 v47, v47
	s_or_b64 exec, exec, s[2:3]
	v_cndmask_b32_e64 v48, 31, 15, s[0:1]
	v_cmp_eq_u32_e32 vcc, 1, v48
	s_nop 1
	v_cndmask_b32_e32 v2, v2, v3, vcc
	v_cmp_eq_u32_e32 vcc, 2, v48
	s_nop 1
	v_cndmask_b32_e32 v2, v2, v4, vcc
	v_cmp_eq_u32_e32 vcc, 3, v48
	s_nop 1
	v_cndmask_b32_e32 v2, v2, v5, vcc
	v_cmp_eq_u32_e32 vcc, 4, v48
	s_nop 1
	v_cndmask_b32_e32 v2, v2, v6, vcc
	v_cmp_eq_u32_e32 vcc, 5, v48
	s_nop 1
	v_cndmask_b32_e32 v2, v2, v7, vcc
	v_cmp_eq_u32_e32 vcc, 6, v48
	s_nop 1
	v_cndmask_b32_e32 v2, v2, v8, vcc
	v_cmp_eq_u32_e32 vcc, 7, v48
	s_nop 1
	v_cndmask_b32_e32 v2, v2, v9, vcc
	v_cmp_eq_u32_e32 vcc, 8, v48
	s_nop 1
	v_cndmask_b32_e32 v2, v2, v10, vcc
	v_cmp_eq_u32_e32 vcc, 9, v48
	s_nop 1
	v_cndmask_b32_e32 v2, v2, v11, vcc
	v_cmp_eq_u32_e32 vcc, 10, v48
	s_nop 1
	v_cndmask_b32_e32 v2, v2, v12, vcc
	v_cmp_eq_u32_e32 vcc, 11, v48
	s_nop 1
	v_cndmask_b32_e32 v2, v2, v13, vcc
	v_cmp_eq_u32_e32 vcc, 12, v48
	s_nop 1
	v_cndmask_b32_e32 v2, v2, v14, vcc
	v_cmp_eq_u32_e32 vcc, 13, v48
	s_nop 1
	v_cndmask_b32_e32 v2, v2, v15, vcc
	v_cmp_eq_u32_e32 vcc, 14, v48
	s_nop 1
	v_cndmask_b32_e32 v2, v2, v16, vcc
	v_cmp_eq_u32_e32 vcc, 15, v48
	s_nop 1
	v_cndmask_b32_e32 v2, v2, v17, vcc
	v_cmp_eq_u32_e32 vcc, 16, v48
	s_nop 1
	v_cndmask_b32_e32 v2, v2, v18, vcc
	v_cmp_eq_u32_e32 vcc, 17, v48
	s_nop 1
	v_cndmask_b32_e32 v2, v2, v19, vcc
	v_cmp_eq_u32_e32 vcc, 18, v48
	s_nop 1
	v_cndmask_b32_e32 v2, v2, v20, vcc
	v_cmp_eq_u32_e32 vcc, 19, v48
	s_nop 1
	v_cndmask_b32_e32 v2, v2, v21, vcc
	v_cmp_eq_u32_e32 vcc, 20, v48
	s_nop 1
	v_cndmask_b32_e32 v2, v2, v22, vcc
	v_cmp_eq_u32_e32 vcc, 21, v48
	s_nop 1
	v_cndmask_b32_e32 v2, v2, v23, vcc
	v_cmp_eq_u32_e32 vcc, 22, v48
	s_nop 1
	v_cndmask_b32_e32 v2, v2, v24, vcc
	v_cmp_eq_u32_e32 vcc, 23, v48
	s_nop 1
	v_cndmask_b32_e32 v2, v2, v25, vcc
	v_cmp_eq_u32_e32 vcc, 24, v48
	s_nop 1
	v_cndmask_b32_e32 v2, v2, v26, vcc
	v_cmp_eq_u32_e32 vcc, 25, v48
	s_nop 1
	v_cndmask_b32_e32 v2, v2, v27, vcc
	v_cmp_eq_u32_e32 vcc, 26, v48
	s_nop 1
	v_cndmask_b32_e32 v2, v2, v28, vcc
	v_cmp_eq_u32_e32 vcc, 27, v48
	s_nop 1
	v_cndmask_b32_e32 v2, v2, v29, vcc
	v_cmp_eq_u32_e32 vcc, 28, v48
	s_nop 1
	v_cndmask_b32_e32 v2, v2, v30, vcc
	v_cmp_eq_u32_e32 vcc, 29, v48
	s_nop 1
	v_cndmask_b32_e32 v2, v2, v31, vcc
	v_cmp_eq_u32_e32 vcc, 30, v48
	s_nop 1
	v_cndmask_b32_e32 v2, v2, v32, vcc
	v_cmp_eq_u32_e32 vcc, 31, v48
	s_nop 1
	v_cndmask_b32_e32 v3, v2, v33, vcc
	v_cmp_ngt_f32_e32 vcc, 1.0, v3
	s_and_saveexec_b64 s[2:3], vcc
	s_xor_b64 s[2:3], exec, s[2:3]
	v_lshrrev_b32_e32 v2, 20, v3
	v_add_u32_e32 v2, 0xfffffc10, v2
	s_andn2_saveexec_b64 s[2:3], s[2:3]
	v_mul_f32_e32 v2, 0x41000000, v3
	v_cvt_i32_f32_e32 v2, v2
	s_or_b64 exec, exec, s[2:3]
	s_waitcnt vmcnt(6)
	v_and_b32_e32 v136, 63, v0
	s_waitcnt vmcnt(2)
	v_lshlrev_b32_e32 v150, 4, v136
	v_and_b32_e32 v3, 0x3e0, v150
	v_add_u32_e32 v18, v1, v3
	v_ashrrev_i32_e32 v1, 6, v0
	v_add_u32_e32 v4, v47, v3
	v_add_u32_e32 v5, v46, v3
	v_add_u32_e32 v6, v45, v3
	v_add_u32_e32 v7, v44, v3
	v_add_u32_e32 v8, v43, v3
	v_add_u32_e32 v9, v42, v3
	v_add_u32_e32 v10, v41, v3
	v_add_u32_e32 v11, v40, v3
	v_add_u32_e32 v12, v39, v3
	v_add_u32_e32 v13, v38, v3
	v_add_u32_e32 v14, v37, v3
	v_add_u32_e32 v15, v36, v3
	v_add_u32_e32 v16, v35, v3
	v_add_u32_e32 v17, v34, v3
	v_add_u32_e32 v2, v2, v3
	v_lshl_add_u32 v151, v1, 13, 0
	v_add_u32_e32 v142, s85, v1
	s_movk_i32 s2, 0x4000
	v_cmp_gt_i32_e32 vcc, s2, v142
	v_lshlrev_b32_e32 v148, 2, v150
	v_lshl_add_u32 v137, v18, 2, v151
	v_lshl_add_u32 v183, v17, 2, v151
	v_lshl_add_u32 v184, v16, 2, v151
	v_lshl_add_u32 v185, v15, 2, v151
	v_lshl_add_u32 v186, v14, 2, v151
	v_lshl_add_u32 v187, v13, 2, v151
	v_lshl_add_u32 v188, v12, 2, v151
	v_lshl_add_u32 v189, v11, 2, v151
	v_lshl_add_u32 v190, v10, 2, v151
	v_lshl_add_u32 v191, v9, 2, v151
	v_lshl_add_u32 v192, v8, 2, v151
	v_lshl_add_u32 v193, v7, 2, v151
	v_lshl_add_u32 v194, v6, 2, v151
	v_lshl_add_u32 v195, v5, 2, v151
	v_lshl_add_u32 v196, v4, 2, v151
	v_lshl_add_u32 v197, v2, 2, v151
	v_mul_u32_u24_e32 v138, 12, v136
	v_and_b32_e32 v199, 2, v0
	v_and_b32_e32 v200, 4, v0
	v_and_b32_e32 v198, 7, v0
	v_lshlrev_b32_e32 v140, 1, v150
	s_and_saveexec_b64 s[8:9], vcc
	s_cbranch_execz .LBB0_3658
	v_readlane_b32 s12, v251, 3
	v_readlane_b32 s13, v251, 4
	v_readlane_b32 s14, v251, 5
	v_readlane_b32 s15, v251, 6
	v_readlane_b32 s16, v251, 7
	v_readlane_b32 s17, v251, 8
	v_mov_b32_e32 v139, 0
	v_readlane_b32 s18, v251, 9
	v_readlane_b32 s19, v251, 10
	v_readlane_b32 s20, v251, 11
	v_readlane_b32 s21, v251, 12
	s_mov_b64 s[10:11], s[14:15]
	s_mov_b64 s[12:13], s[16:17]
	v_mov_b32_e32 v141, v139
	v_mov_b32_e32 v149, v139
	v_readlane_b32 s23, v251, 14
	v_readlane_b32 s25, v251, 16
	v_readlane_b32 s27, v251, 18
	s_mov_b64 s[14:15], s[18:19]
	s_mov_b64 s[16:17], s[20:21]
	v_add_u32_e32 v201, v151, v148
	v_cmp_eq_u32_e32 vcc, 0, v199
	v_cmp_eq_u32_e64 s[4:5], 0, v200
	v_lshl_add_u64 v[144:145], s[68:69], 0, v[140:141]
	v_lshl_add_u64 v[146:147], s[74:75], 0, v[140:141]
	v_lshl_add_u64 v[152:153], s[78:79], 0, v[138:139]
	s_waitcnt vmcnt(1)
	v_lshl_add_u64 v[154:155], s[80:81], 0, v[138:139]
	v_lshl_add_u64 v[156:157], s[10:11], 0, v[148:149]
	s_waitcnt vmcnt(0)
	v_lshl_add_u64 v[158:159], s[12:13], 0, v[148:149]
	v_lshl_add_u64 v[160:161], s[14:15], 0, v[148:149]
	s_mov_b64 s[10:11], 0
	s_mov_b32 s7, 0x378e98ab
	s_mov_b32 s13, 0x3b7cd369
	s_mov_b32 s17, 0xbcc618b2
	s_mov_b32 s19, 0x3dda74e4
	s_mov_b32 s21, 0x3f228afd
	s_mov_b32 s23, 0x3e03c728
	s_mov_b32 s25, 0xbfb8aa3b
	s_mov_b32 s27, 0x42ce8ed0
	s_mov_b32 s28, 0xc2b17218
	v_mov_b32_e32 v141, 0x3ba10414
	s_brev_b32 s29, -2
	s_mov_b32 s12, 0x3f9837f0
	v_mov_b32_e32 v149, 0x3727c5ac
	s_mov_b32 s30, 0x800000
	s_movk_i32 s31, 0x3fff
	v_mov_b32_e32 v202, 0x300
	v_mov_b32_e32 v203, 0xb9c68948
	v_mov_b32_e32 v204, 0x7f800000
	v_readlane_b32 s22, v251, 13
	v_readlane_b32 s24, v251, 15
	v_readlane_b32 s26, v251, 17
	v_readfirstlane_b32 s52, v142
	v_lshrrev_b32_e32 v248, 3, v136
	s_branch .LpA_hdr
.LpA_epi:
	v_lshlrev_b64 v[10:11], 9, v[142:143]
	v_lshl_or_b32 v10, v136, 2, v10
	v_lshl_add_u64 v[20:21], s[64:65], 0, v[10:11]
	global_store_dword v[20:21], v249, off
	global_store_dword v[20:21], v255, off offset:256
	v_add_u32_e32 v142, s6, v142
	v_cmp_lt_i32_e64 s[2:3], s31, v142
	s_nop 0
	s_or_b64 s[10:11], s[2:3], s[10:11]
	s_andn2_b64 exec, exec, s[10:11]
	s_cbranch_execz .LpA_done
.LpA_hdr:
	v_ashrrev_i32_e32 v143, 31, v142
	v_lshlrev_b64 v[164:165], 11, v[142:143]
	v_lshl_add_u64 v[162:163], v[144:145], 0, v[164:165]
	global_load_dwordx4 v[2:5], v[162:163], off
	global_load_dwordx4 v[6:9], v[162:163], off offset:16
	v_lshlrev_b64 v[10:11], 9, v[142:143]
	v_lshl_or_b32 v10, v136, 2, v10
	v_lshl_add_u64 v[18:19], s[82:83], 0, v[10:11]
	v_lshl_add_u64 v[20:21], s[64:65], 0, v[10:11]
	s_mov_b32 s33, 0
	s_mov_b32 s34, 0
	v_mov_b32_e32 v180, 0
	v_mov_b32_e32 v181, v139
	v_mov_b32_e32 v178, 0
	v_mov_b32_e32 v179, v139
	v_mov_b32_e32 v176, 0
	v_mov_b32_e32 v177, v139
	v_mov_b32_e32 v174, 0
	v_mov_b32_e32 v175, v139
	v_mov_b32_e32 v172, 0
	v_mov_b32_e32 v173, v139
	v_mov_b32_e32 v170, 0
	v_mov_b32_e32 v171, v139
	v_mov_b32_e32 v168, 0
	v_mov_b32_e32 v169, v139
	v_mov_b32_e32 v166, 0
	v_mov_b32_e32 v167, v139
	s_waitcnt vmcnt(1)
	v_lshlrev_b32_e32 v10, 16, v2
	v_and_b32_e32 v11, 0xffff0000, v2
	v_lshlrev_b32_e32 v12, 16, v3
	v_and_b32_e32 v13, 0xffff0000, v3
	v_lshlrev_b32_e32 v2, 16, v4
	v_and_b32_e32 v3, 0xffff0000, v4
	v_lshlrev_b32_e32 v4, 16, v5
	v_and_b32_e32 v5, 0xffff0000, v5
	s_waitcnt vmcnt(0)
	v_lshlrev_b32_e32 v14, 16, v6
	v_and_b32_e32 v15, 0xffff0000, v6
	v_lshlrev_b32_e32 v16, 16, v7
	v_and_b32_e32 v17, 0xffff0000, v7
	v_lshlrev_b32_e32 v6, 16, v8
	v_and_b32_e32 v7, 0xffff0000, v8
	v_lshlrev_b32_e32 v8, 16, v9
	v_and_b32_e32 v9, 0xffff0000, v9
	ds_write_b128 v201, v[10:13]
	ds_write_b128 v201, v[2:5] offset:16
	ds_write_b128 v201, v[14:17] offset:32
	ds_write_b128 v201, v[6:9] offset:48
	global_load_dword v211, v[18:19], off
	global_load_dword v212, v[18:19], off offset:256
	global_load_dword v213, v[20:21], off
	global_load_dword v214, v[20:21], off offset:256
	v_and_b32_e32 v3, 64, v182
	ds_read_b32 v232, v137
	ds_read_b32 v233, v183
	ds_read_b32 v234, v184
	ds_read_b32 v235, v185
	ds_read_b32 v236, v186
	ds_read_b32 v237, v187
	ds_read_b32 v238, v188
	ds_read_b32 v239, v189
	ds_read_b32 v240, v190
	ds_read_b32 v241, v191
	ds_read_b32 v242, v192
	ds_read_b32 v243, v193
	ds_read_b32 v244, v194
	ds_read_b32 v245, v195
	ds_read_b32 v246, v196
	ds_read_b32 v247, v197
	v_xor_b32_e32 v2, 1, v182
	v_add_u32_e32 v4, 64, v3
	v_cmp_lt_i32_e64 s[2:3], v2, v4
	v_or_b32_e32 v231, v198, v3
	s_nop 0
	v_cndmask_b32_e64 v2, v182, v2, s[2:3]
	v_lshlrev_b32_e32 v205, 2, v2
	v_xor_b32_e32 v2, 2, v182
	v_cmp_lt_i32_e64 s[2:3], v2, v4
	s_nop 1
	v_cndmask_b32_e64 v2, v182, v2, s[2:3]
	v_lshlrev_b32_e32 v206, 2, v2
	v_xor_b32_e32 v2, 4, v182
	v_cmp_lt_i32_e64 s[2:3], v2, v4
	s_nop 1
	v_cndmask_b32_e64 v2, v182, v2, s[2:3]
	v_lshlrev_b32_e32 v207, 2, v2
	v_xor_b32_e32 v2, 8, v182
	v_cmp_lt_i32_e64 s[2:3], v2, v4
	s_nop 1
	v_cndmask_b32_e64 v2, v182, v2, s[2:3]
	v_lshlrev_b32_e32 v208, 2, v2
	v_xor_b32_e32 v2, 16, v182
	v_cmp_lt_i32_e64 s[2:3], v2, v4
	s_nop 1
	v_cndmask_b32_e64 v2, v182, v2, s[2:3]
	v_lshlrev_b32_e32 v209, 2, v2
	v_xor_b32_e32 v2, 32, v182
	v_cmp_lt_i32_e64 s[2:3], v2, v4
	s_nop 1
	v_cndmask_b32_e64 v2, v182, v2, s[2:3]
	v_lshlrev_b32_e32 v210, 2, v2

.LpA_half:
	s_cmp_lt_u32 s34, 8
	s_cselect_b64 s[2:3], -1, 0
	s_waitcnt vmcnt(8)
	s_waitcnt lgkmcnt(0)
	v_mov_b32_e32 v51, v2
	v_mov_b32_e32 v52, v3
	v_mov_b32_e32 v53, v4
	v_cvt_scalef32_pk32_f32_fp6 v[2:33], v[48:53], 1.0
	v_pk_mul_f32 v[108:109], v[232:233], v[2:3]
	v_pk_mul_f32 v[110:111], v[232:233], v[18:19]
	v_pk_fma_f32 v[108:109], v[234:235], v[4:5], v[108:109]
	v_pk_fma_f32 v[110:111], v[234:235], v[20:21], v[110:111]
	v_pk_fma_f32 v[108:109], v[236:237], v[6:7], v[108:109]
	v_pk_fma_f32 v[110:111], v[236:237], v[22:23], v[110:111]
	v_pk_fma_f32 v[108:109], v[238:239], v[8:9], v[108:109]
	v_pk_fma_f32 v[110:111], v[238:239], v[24:25], v[110:111]
	v_pk_fma_f32 v[108:109], v[240:241], v[10:11], v[108:109]
	v_pk_fma_f32 v[110:111], v[240:241], v[26:27], v[110:111]
	v_pk_fma_f32 v[108:109], v[242:243], v[12:13], v[108:109]
	v_pk_fma_f32 v[110:111], v[242:243], v[28:29], v[110:111]
	v_pk_fma_f32 v[108:109], v[244:245], v[14:15], v[108:109]
	v_pk_fma_f32 v[110:111], v[244:245], v[30:31], v[110:111]
	v_pk_fma_f32 v[108:109], v[246:247], v[16:17], v[108:109]
	v_pk_fma_f32 v[110:111], v[246:247], v[32:33], v[110:111]
	s_nop 0
	v_add_f32_e32 v37, v108, v109
	v_add_f32_e32 v38, v110, v111
	v_mov_b32_e32 v57, v80
	v_mov_b32_e32 v58, v81
	v_mov_b32_e32 v59, v82
	v_cvt_scalef32_pk32_f32_fp6 v[2:33], v[54:59], 1.0
	v_pk_mul_f32 v[108:109], v[232:233], v[2:3]
	v_pk_mul_f32 v[110:111], v[232:233], v[18:19]
	v_pk_fma_f32 v[108:109], v[234:235], v[4:5], v[108:109]
	v_pk_fma_f32 v[110:111], v[234:235], v[20:21], v[110:111]
	v_pk_fma_f32 v[108:109], v[236:237], v[6:7], v[108:109]
	v_pk_fma_f32 v[110:111], v[236:237], v[22:23], v[110:111]
	v_pk_fma_f32 v[108:109], v[238:239], v[8:9], v[108:109]
	v_pk_fma_f32 v[110:111], v[238:239], v[24:25], v[110:111]
	v_pk_fma_f32 v[108:109], v[240:241], v[10:11], v[108:109]
	v_pk_fma_f32 v[110:111], v[240:241], v[26:27], v[110:111]
	v_pk_fma_f32 v[108:109], v[242:243], v[12:13], v[108:109]
	v_pk_fma_f32 v[110:111], v[242:243], v[28:29], v[110:111]
	v_pk_fma_f32 v[108:109], v[244:245], v[14:15], v[108:109]
	v_pk_fma_f32 v[110:111], v[244:245], v[30:31], v[110:111]
	v_pk_fma_f32 v[108:109], v[246:247], v[16:17], v[108:109]
	v_pk_fma_f32 v[110:111], v[246:247], v[32:33], v[110:111]
	s_nop 0
	v_add_f32_e32 v39, v108, v109
	v_add_f32_e32 v43, v110, v111
	v_mov_b32_e32 v63, v84
	v_mov_b32_e32 v64, v85
	v_mov_b32_e32 v65, v86
	v_cvt_scalef32_pk32_f32_fp6 v[2:33], v[60:65], 1.0
	v_pk_mul_f32 v[108:109], v[232:233], v[2:3]
	v_pk_mul_f32 v[110:111], v[232:233], v[18:19]
	v_pk_fma_f32 v[108:109], v[234:235], v[4:5], v[108:109]
	v_pk_fma_f32 v[110:111], v[234:235], v[20:21], v[110:111]
	v_pk_fma_f32 v[108:109], v[236:237], v[6:7], v[108:109]
	v_pk_fma_f32 v[110:111], v[236:237], v[22:23], v[110:111]
	v_pk_fma_f32 v[108:109], v[238:239], v[8:9], v[108:109]
	v_pk_fma_f32 v[110:111], v[238:239], v[24:25], v[110:111]
	v_pk_fma_f32 v[108:109], v[240:241], v[10:11], v[108:109]
	v_pk_fma_f32 v[110:111], v[240:241], v[26:27], v[110:111]
	v_pk_fma_f32 v[108:109], v[242:243], v[12:13], v[108:109]
	v_pk_fma_f32 v[110:111], v[242:243], v[28:29], v[110:111]
	v_pk_fma_f32 v[108:109], v[244:245], v[14:15], v[108:109]
	v_pk_fma_f32 v[110:111], v[244:245], v[30:31], v[110:111]
	v_pk_fma_f32 v[108:109], v[246:247], v[16:17], v[108:109]
	v_pk_fma_f32 v[110:111], v[246:247], v[32:33], v[110:111]
	s_nop 0
	v_add_f32_e32 v47, v108, v109
	v_add_f32_e32 v48, v110, v111
	v_mov_b32_e32 v79, v88
	v_mov_b32_e32 v80, v89
	v_mov_b32_e32 v81, v90
	v_cvt_scalef32_pk32_f32_fp6 v[2:33], v[76:81], 1.0
	v_pk_mul_f32 v[108:109], v[232:233], v[2:3]
	v_pk_mul_f32 v[110:111], v[232:233], v[18:19]
	v_pk_fma_f32 v[108:109], v[234:235], v[4:5], v[108:109]
	v_pk_fma_f32 v[110:111], v[234:235], v[20:21], v[110:111]
	v_pk_fma_f32 v[108:109], v[236:237], v[6:7], v[108:109]
	v_pk_fma_f32 v[110:111], v[236:237], v[22:23], v[110:111]
	v_pk_fma_f32 v[108:109], v[238:239], v[8:9], v[108:109]
	v_pk_fma_f32 v[110:111], v[238:239], v[24:25], v[110:111]
	v_pk_fma_f32 v[108:109], v[240:241], v[10:11], v[108:109]
	v_pk_fma_f32 v[110:111], v[240:241], v[26:27], v[110:111]
	v_pk_fma_f32 v[108:109], v[242:243], v[12:13], v[108:109]
	v_pk_fma_f32 v[110:111], v[242:243], v[28:29], v[110:111]
	v_pk_fma_f32 v[108:109], v[244:245], v[14:15], v[108:109]
	v_pk_fma_f32 v[110:111], v[244:245], v[30:31], v[110:111]
	v_pk_fma_f32 v[108:109], v[246:247], v[16:17], v[108:109]
	v_pk_fma_f32 v[110:111], v[246:247], v[32:33], v[110:111]
	s_nop 0
	v_add_f32_e32 v2, v108, v109
	v_add_f32_e32 v18, v110, v111
	v_cndmask_b32_e64 v3, v37, v38, s[0:1]
	v_cndmask_b32_e64 v5, v39, v43, s[0:1]
	v_cndmask_b32_e64 v6, v47, v48, s[0:1]
	v_cndmask_b32_e64 v7, v2, v18, s[0:1]
	v_cndmask_b32_e64 v4, v38, v37, s[0:1]
	s_nop 0
	v_mov_b32_dpp v3, v3 quad_perm:[1,0,3,2] row_mask:0xf bank_mask:0xf
	v_mov_b32_dpp v5, v5 quad_perm:[1,0,3,2] row_mask:0xf bank_mask:0xf
	v_mov_b32_dpp v6, v6 quad_perm:[1,0,3,2] row_mask:0xf bank_mask:0xf
	v_mov_b32_dpp v7, v7 quad_perm:[1,0,3,2] row_mask:0xf bank_mask:0xf
	v_add_f32_e32 v3, v4, v3
	v_cndmask_b32_e64 v4, v43, v39, s[0:1]
	v_add_f32_e32 v4, v4, v5
	v_cndmask_b32_e64 v5, v48, v47, s[0:1]
	v_cndmask_b32_e64 v2, v18, v2, s[0:1]
	v_add_f32_e32 v5, v5, v6
	v_add_f32_e32 v2, v2, v7
	v_cndmask_b32_e32 v6, v3, v4, vcc
	v_cndmask_b32_e32 v7, v5, v2, vcc
	v_cndmask_b32_e32 v3, v4, v3, vcc
	v_cndmask_b32_e32 v2, v2, v5, vcc
	v_and_or_b32 v5, s33, 56, v231
	v_mov_b32_dpp v6, v6 quad_perm:[2,3,0,1] row_mask:0xf bank_mask:0xf
	v_mov_b32_dpp v7, v7 quad_perm:[2,3,0,1] row_mask:0xf bank_mask:0xf
	v_add_f32_e32 v3, v3, v6
	v_add_f32_e32 v2, v2, v7
	v_cndmask_b32_e64 v4, v3, v2, s[4:5]
	v_cndmask_b32_e64 v2, v2, v3, s[4:5]
	v_lshlrev_b32_e32 v5, 2, v5
	v_cndmask_b32_e64 v7, v214, v213, s[2:3]
	v_mov_b32_dpp v6, v4 row_shl:4 row_mask:0xf bank_mask:0x5
	v_mov_b32_dpp v6, v4 row_shr:4 row_mask:0xf bank_mask:0xa
	ds_bpermute_b32 v7, v5, v7
	v_add_f32_e32 v2, v2, v6
	s_nop 1
	v_mov_b32_dpp v3, v2 row_ror:8 row_mask:0xf bank_mask:0xf
	v_add_f32_e32 v2, v2, v3
	ds_bpermute_b32 v3, v209, v2
	s_waitcnt lgkmcnt(0)
	v_add_f32_e32 v3, v2, v3
	v_mov_b32_e32 v2, v7
	v_mov_b32_e32 v4, v3
	s_nop 1
	v_permlane32_swap_b32 v3, v4
	v_add_f32_e32 v3, v3, v4
	v_mul_f32_e32 v3, 0x3caaaaab, v3
	v_mul_f32_e32 v4, 0x3f3504f3, v3
	v_cmp_nlt_f32_e64 s[2:3], |v4|, 1.0
	s_and_saveexec_b64 s[14:15], s[2:3]
	s_xor_b64 s[14:15], exec, s[14:15]
	s_cbranch_execz .LpA_erf_else
	v_fma_f32 v5, |v4|, s7, v203
	v_fma_f32 v5, |v4|, v5, s13
	v_fma_f32 v5, |v4|, v5, s17
	v_fma_f32 v5, |v4|, v5, s19
	v_fma_f32 v5, |v4|, v5, s21
	v_fma_f32 v5, |v4|, v5, s23
	v_fma_f32 v5, |v4|, v5, |v4|
	v_mul_f32_e32 v6, 0xbfb8aa3b, v5
	v_fma_f32 v7, v5, s25, -v6
	v_rndne_f32_e32 v8, v6
	v_fmac_f32_e32 v7, 0xb2a5705f, v5
	v_sub_f32_e32 v6, v6, v8
	v_add_f32_e32 v6, v6, v7
	v_cvt_i32_f32_e32 v7, v8
	v_exp_f32_e32 v6, v6
	v_cmp_nlt_f32_e64 s[2:3], s27, v5
	v_ldexp_f32 v6, v6, v7
	s_nop 0
	v_cndmask_b32_e64 v6, 0, v6, s[2:3]
	v_cmp_ngt_f32_e64 s[2:3], s28, v5
	s_nop 1
	v_cndmask_b32_e64 v5, v204, v6, s[2:3]
	v_sub_f32_e32 v5, 1.0, v5

.LpA_erf_join:
	s_or_b64 exec, exec, s[2:3]
	s_waitcnt lgkmcnt(0)
	v_mul_f32_e32 v2, 0.5, v2
	v_mul_f32_e32 v2, v2, v3
	v_bfi_b32 v3, s29, v5, v4
	v_add_f32_e32 v3, 1.0, v3
	v_mul_f32_e32 v2, v2, v3
	v_mul_f32_e32 v107, 0x3e124925, v2
	v_cmp_eq_u32_e64 s[54:55], s34, v248
	s_sub_i32 s53, s34, 8
	v_cmp_eq_u32_e64 s[56:57], s53, v248
	s_nop 1
	v_cndmask_b32_e64 v249, v249, v107, s[54:55]
	v_cndmask_b32_e64 v255, v255, v107, s[56:57]
	s_add_i32 s34, s34, 1
	s_add_i32 s33, s33, 8
	s_bitcmp1_b32 s34, 0
	s_cbranch_scc0 .LpA_pair_done
	s_waitcnt vmcnt(0)
	v_mov_b32_e32 v48, v34
	v_mov_b32_e32 v49, v35
	v_mov_b32_e32 v50, v36
	v_mov_b32_e32 v2, v44
	v_mov_b32_e32 v3, v45
	v_mov_b32_e32 v4, v46
	v_mov_b32_e32 v54, v66
	v_mov_b32_e32 v55, v67
	v_mov_b32_e32 v56, v68
	v_mov_b32_e32 v80, v40
	v_mov_b32_e32 v81, v41
	v_mov_b32_e32 v82, v42
	v_mov_b32_e32 v60, v98
	v_mov_b32_e32 v61, v99
	v_mov_b32_e32 v62, v100
	v_mov_b32_e32 v84, v72
	v_mov_b32_e32 v85, v73
	v_mov_b32_e32 v86, v74
	v_mov_b32_e32 v76, v130
	v_mov_b32_e32 v77, v131
	v_mov_b32_e32 v78, v132
	v_mov_b32_e32 v88, v104
	v_mov_b32_e32 v89, v105
	v_mov_b32_e32 v90, v106
	s_branch .LpA_half
